# static-priority lever: removed the redundant mid-block s_setprio 0/1 flip pair inside each 32-MFMA block of the six GEMM K-loops; otherwise v19
# speedup vs baseline: 1.0016x; 1.0016x over previous
; #define PG8_STAGE(bufoff, gbase, voff) do { _Pragma("unroll") for (int _i = 0; _i < 2; ++_i) _Pragma("unroll") for (int _r = 0; _r < PG8_NREP; ++_r) \
;         __builtin_amdgcn_global_load_lds((const unsigned*)((const char*)(gbase) + (voff)[_i]), (PG8_LAS unsigned*)(lds + (bufoff) + ldsw + _i * 8192), 16, 0, 0); } while (0)
; #define PG8_LDA(dst, b, h) do { _Pragma("unroll") for (int m = 0; m < 4; ++m) _Pragma("unroll") for (int k = 0; k < 2; ++k) { dst[m][k] = *(const PG8_LAS bf16x8*)(lds + PG8_SA(b, h) + aoff + m * 2048 + k * 1024); PG8_DUP((unsigned)(uintptr_t)(lds + PG8_SA(b, h) + aoff + m * 2048 + k * 1024)); } } while (0)
; #define PG8_LDB(dst, b, h) do { _Pragma("unroll") for (int n = 0; n < 2; ++n) _Pragma("unroll") for (int k = 0; k < 2; ++k) { dst[n][k] = *(const PG8_LAS bf16x8*)(lds + PG8_SB(b, h) + boff + n * 2048 + k * 1024); PG8_DUP((unsigned)(uintptr_t)(lds + PG8_SB(b, h) + boff + n * 2048 + k * 1024)); } } while (0)
; #define PG8_MMA(ai, bj, At, Bt) do { __builtin_amdgcn_s_setprio(1); _Pragma("unroll") for (int m = 0; m < 4; ++m) _Pragma("unroll") for (int n = 0; n < 2; ++n) _Pragma("unroll") for (int k = 0; k < 2; ++k) \
;         acc[ai][bj][m][n] = __builtin_amdgcn_mfma_f32_16x16x32_bf16(Bt[n][k], At[m][k], acc[ai][bj][m][n], 0, 0, 0); __builtin_amdgcn_s_setprio(0); } while (0)
; #define PG8_WAIT_V(n) do { if ((n) == 0) asm volatile("s_waitcnt vmcnt(0)" ::: "memory"); else if ((n) == 2) asm volatile("s_waitcnt vmcnt(4)" ::: "memory"); else if ((n) == 4) asm volatile("s_waitcnt vmcnt(8)" ::: "memory"); \
;     else if ((n) == 6) asm volatile("s_waitcnt vmcnt(12)" ::: "memory"); else asm volatile("s_waitcnt vmcnt(16)" ::: "memory"); } while (0)
; #define PG8_WAIT_V(n) asm volatile("s_waitcnt vmcnt(" #n ")" ::: "memory")
; template <class Epi, class Sched, bool ALIGN_EPI = false, bool SP2 = false>
; __device__ __forceinline__ void gemm_phase(PG8_LAS unsigned char* lds, const Gemm g, const Sched& S, const Epi& E) {
;     ...
;             PG8_LDB(B0, 0, 0); PG8_LDB(B1, 0, 1); PG8_SCHED; PG8_LDA(At, 0, 0); PG8_STAGE(PG8_SA(1, 1), a1 + hstepA, voffA);
;             PG8_WAIT_V(8); PG8_WAIT_L(0); PG8_BAR; PG8_MMA(0, 0, At, B0); PG8_MMA(0, 1, At, B1); PG8_BAR; PG8_SCHED;
;             PG8_LDA(At, 0, 1); PG8_STAGE(PG8_SB(0, 0), b2, voffB); PG8_STAGE(PG8_SB(0, 1), b2 + hstepB, voffB); PG8_STAGE(PG8_SA(0, 0), a2, voffA);
.LBB0_156:
	s_add_u32 s26, s44, 0xfff80080
	s_addc_u32 s27, s45, -1
	s_add_i32 s28, 0, 0x10000
	s_cmp_eq_u32 s25, 28
	s_cselect_b32 s95, s15, s27
	s_cselect_b32 s94, s86, s26
	s_cselect_b32 s47, s63, s24
	s_cselect_b32 s46, vcc_lo, vcc_hi
	s_add_i32 s29, 0, 0x14000
	v_add_u32_e32 v76, s28, v161
	v_add_u32_e32 v158, s29, v161
	ds_read_b128 v[60:63], v76
	ds_read_b128 v[68:71], v76 offset:1024
	ds_read_b128 v[72:75], v76 offset:2048
	ds_read_b128 v[76:79], v76 offset:3072
	ds_read_b128 v[154:157], v158
	ds_read_b128 v[164:167], v158 offset:1024
	ds_read_b128 v[168:171], v158 offset:2048
	ds_read_b128 v[172:175], v158 offset:3072
	v_lshl_add_u64 v[158:159], s[44:45], 0, v[150:151]
	s_add_i32 m0, s17, 0xc000
	ds_read_b128 v[176:179], v163
	ds_read_b128 v[180:183], v163 offset:1024
	ds_read_b128 v[184:187], v163 offset:2048
	ds_read_b128 v[188:191], v163 offset:3072
	ds_read_b128 v[210:213], v163 offset:4096
	ds_read_b128 v[214:217], v163 offset:5120
	ds_read_b128 v[218:221], v163 offset:6144
	ds_read_b128 v[222:225], v163 offset:7168
	global_load_lds_dwordx4 v[158:159], off
	v_lshl_add_u64 v[158:159], s[44:45], 0, v[152:153]
	s_add_i32 m0, s17, 0xe000
	s_nop 0
	global_load_lds_dwordx4 v[158:159], off
	s_waitcnt vmcnt(8)
	s_waitcnt lgkmcnt(0)
	s_barrier
	s_setprio 1
	s_waitcnt lgkmcnt(0)
	v_mfma_f32_16x16x32_bf16 v[140:143], v[60:63], v[176:179], v[140:143]
	v_mfma_f32_16x16x32_bf16 v[136:139], v[72:75], v[176:179], v[136:139]
	v_mfma_f32_16x16x32_bf16 v[124:127], v[60:63], v[184:187], v[124:127]
	v_mfma_f32_16x16x32_bf16 v[120:123], v[72:75], v[184:187], v[120:123]
	v_mfma_f32_16x16x32_bf16 v[108:111], v[60:63], v[210:213], v[108:111]
	v_mfma_f32_16x16x32_bf16 v[104:107], v[72:75], v[210:213], v[104:107]
	v_mfma_f32_16x16x32_bf16 v[92:95], v[60:63], v[218:221], v[92:95]
	v_mfma_f32_16x16x32_bf16 v[88:91], v[72:75], v[218:221], v[88:91]
	v_mfma_f32_16x16x32_bf16 v[140:143], v[68:71], v[180:183], v[140:143]
	v_mfma_f32_16x16x32_bf16 v[136:139], v[76:79], v[180:183], v[136:139]
	v_mfma_f32_16x16x32_bf16 v[124:127], v[68:71], v[188:191], v[124:127]
	v_mfma_f32_16x16x32_bf16 v[120:123], v[76:79], v[188:191], v[120:123]
	v_mfma_f32_16x16x32_bf16 v[108:111], v[68:71], v[214:217], v[108:111]
	v_mfma_f32_16x16x32_bf16 v[104:107], v[76:79], v[214:217], v[104:107]
	v_mfma_f32_16x16x32_bf16 v[92:95], v[68:71], v[222:225], v[92:95]
	v_mfma_f32_16x16x32_bf16 v[88:91], v[76:79], v[222:225], v[88:91]
	v_mfma_f32_16x16x32_bf16 v[132:135], v[154:157], v[176:179], v[132:135]
	v_mfma_f32_16x16x32_bf16 v[128:131], v[168:171], v[176:179], v[128:131]
	v_mfma_f32_16x16x32_bf16 v[116:119], v[154:157], v[184:187], v[116:119]
	v_mfma_f32_16x16x32_bf16 v[112:115], v[168:171], v[184:187], v[112:115]
	v_mfma_f32_16x16x32_bf16 v[100:103], v[154:157], v[210:213], v[100:103]
	v_mfma_f32_16x16x32_bf16 v[96:99], v[168:171], v[210:213], v[96:99]
	v_mfma_f32_16x16x32_bf16 v[84:87], v[154:157], v[218:221], v[84:87]
	v_mfma_f32_16x16x32_bf16 v[80:83], v[168:171], v[218:221], v[80:83]
	v_mfma_f32_16x16x32_bf16 v[132:135], v[164:167], v[180:183], v[132:135]
	v_mfma_f32_16x16x32_bf16 v[128:131], v[172:175], v[180:183], v[128:131]
	v_mfma_f32_16x16x32_bf16 v[116:119], v[164:167], v[188:191], v[116:119]
	v_mfma_f32_16x16x32_bf16 v[112:115], v[172:175], v[188:191], v[112:115]
	v_mfma_f32_16x16x32_bf16 v[100:103], v[164:167], v[214:217], v[100:103]
	v_mfma_f32_16x16x32_bf16 v[96:99], v[172:175], v[214:217], v[96:99]
	v_mfma_f32_16x16x32_bf16 v[84:87], v[164:167], v[222:225], v[84:87]
	v_mfma_f32_16x16x32_bf16 v[80:83], v[172:175], v[222:225], v[80:83]
	s_setprio 0
	s_barrier
	s_add_i32 s26, s28, s16
	v_lshl_add_u64 v[158:159], s[46:47], 0, v[192:193]
	s_mov_b32 m0, s26
	ds_read_b128 v[176:179], v163 offset:16384
	ds_read_b128 v[180:183], v163 offset:17408
	ds_read_b128 v[184:187], v163 offset:18432
	ds_read_b128 v[188:191], v163 offset:19456
	ds_read_b128 v[210:213], v163 offset:20480
	ds_read_b128 v[214:217], v163 offset:21504
	ds_read_b128 v[218:221], v163 offset:22528
	ds_read_b128 v[222:225], v163 offset:23552
	global_load_lds_dwordx4 v[158:159], off
	s_add_i32 m0, s26, 0x2000
	s_add_u32 s26, s46, 0x80000
	v_lshl_add_u64 v[194:195], s[46:47], 0, v[144:145]
	s_addc_u32 s27, s47, 0
	s_add_i32 s28, s29, s16
	global_load_lds_dwordx4 v[194:195], off
	v_lshl_add_u64 v[196:197], s[26:27], 0, v[192:193]
	s_mov_b32 m0, s28
	v_lshl_add_u64 v[200:201], s[94:95], 0, v[146:147]
	global_load_lds_dwordx4 v[196:197], off
	v_lshl_add_u64 v[196:197], s[26:27], 0, v[144:145]
	s_add_i32 m0, s28, 0x2000
	s_nop 0
	global_load_lds_dwordx4 v[196:197], off
	v_lshl_add_u64 v[196:197], s[94:95], 0, v[148:149]
	s_mov_b32 m0, s17
	s_nop 0
	global_load_lds_dwordx4 v[196:197], off
	s_mov_b32 m0, s18
	s_nop 0
	global_load_lds_dwordx4 v[200:201], off
	s_waitcnt vmcnt(8)
	s_waitcnt lgkmcnt(0)
	s_barrier
; #define PG8_STAGE(bufoff, gbase, voff) do { _Pragma("unroll") for (int _i = 0; _i < 2; ++_i) _Pragma("unroll") for (int _r = 0; _r < PG8_NREP; ++_r) \
;         __builtin_amdgcn_global_load_lds((const unsigned*)((const char*)(gbase) + (voff)[_i]), (PG8_LAS unsigned*)(lds + (bufoff) + ldsw + _i * 8192), 16, 0, 0); } while (0)
; #define PG8_LDA(dst, b, h) do { _Pragma("unroll") for (int m = 0; m < 4; ++m) _Pragma("unroll") for (int k = 0; k < 2; ++k) { dst[m][k] = *(const PG8_LAS bf16x8*)(lds + PG8_SA(b, h) + aoff + m * 2048 + k * 1024); PG8_DUP((unsigned)(uintptr_t)(lds + PG8_SA(b, h) + aoff + m * 2048 + k * 1024)); } } while (0)
; #define PG8_LDB(dst, b, h) do { _Pragma("unroll") for (int n = 0; n < 2; ++n) _Pragma("unroll") for (int k = 0; k < 2; ++k) { dst[n][k] = *(const PG8_LAS bf16x8*)(lds + PG8_SB(b, h) + boff + n * 2048 + k * 1024); PG8_DUP((unsigned)(uintptr_t)(lds + PG8_SB(b, h) + boff + n * 2048 + k * 1024)); } } while (0)
; #define PG8_MMA(ai, bj, At, Bt) do { __builtin_amdgcn_s_setprio(1); _Pragma("unroll") for (int m = 0; m < 4; ++m) _Pragma("unroll") for (int n = 0; n < 2; ++n) _Pragma("unroll") for (int k = 0; k < 2; ++k) \
;         acc[ai][bj][m][n] = __builtin_amdgcn_mfma_f32_16x16x32_bf16(Bt[n][k], At[m][k], acc[ai][bj][m][n], 0, 0, 0); __builtin_amdgcn_s_setprio(0); } while (0)
; #define PG8_WAIT_V(n) do { if ((n) == 0) asm volatile("s_waitcnt vmcnt(0)" ::: "memory"); else if ((n) == 2) asm volatile("s_waitcnt vmcnt(4)" ::: "memory"); else if ((n) == 4) asm volatile("s_waitcnt vmcnt(8)" ::: "memory"); \
;     else if ((n) == 6) asm volatile("s_waitcnt vmcnt(12)" ::: "memory"); else asm volatile("s_waitcnt vmcnt(16)" ::: "memory"); } while (0)
; #define PG8_WAIT_V(n) asm volatile("s_waitcnt vmcnt(" #n ")" ::: "memory")
; #define PG8_BAR __builtin_amdgcn_s_barrier()
; template <class Epi, class Sched, bool ALIGN_EPI = false, bool SP2 = false>
; __device__ __forceinline__ void gemm_phase(PG8_LAS unsigned char* lds, const Gemm g, const Sched& S, const Epi& E) {
;     ...
;             PG8_WAIT_V(8); PG8_WAIT_L(0); PG8_BAR; PG8_MMA(1, 0, At, B0); PG8_MMA(1, 1, At, B1); PG8_BAR; PG8_SCHED;
;             PG8_LDB(B0, 1, 0); PG8_LDB(B1, 1, 1); PG8_SCHED; PG8_LDA(At, 1, 0); PG8_STAGE(PG8_SA(0, 1), a2 + hstepA, voffA);
;             PG8_WAIT_V(8); PG8_WAIT_L(0); PG8_BAR; PG8_MMA(0, 0, At, B0); PG8_MMA(0, 1, At, B1); PG8_BAR; PG8_SCHED;
	s_setprio 1
	s_waitcnt lgkmcnt(0)
	v_mfma_f32_16x16x32_bf16 v[64:67], v[60:63], v[176:179], v[64:67]
	v_mfma_f32_16x16x32_bf16 v[56:59], v[72:75], v[176:179], v[56:59]
	v_mfma_f32_16x16x32_bf16 v[44:47], v[60:63], v[184:187], v[44:47]
	v_mfma_f32_16x16x32_bf16 v[40:43], v[72:75], v[184:187], v[40:43]
	v_mfma_f32_16x16x32_bf16 v[28:31], v[60:63], v[210:213], v[28:31]
	v_mfma_f32_16x16x32_bf16 v[24:27], v[72:75], v[210:213], v[24:27]
	v_mfma_f32_16x16x32_bf16 v[12:15], v[60:63], v[218:221], v[12:15]
	v_mfma_f32_16x16x32_bf16 v[8:11], v[72:75], v[218:221], v[8:11]
	v_mfma_f32_16x16x32_bf16 v[64:67], v[68:71], v[180:183], v[64:67]
	v_mfma_f32_16x16x32_bf16 v[56:59], v[76:79], v[180:183], v[56:59]
	v_mfma_f32_16x16x32_bf16 v[44:47], v[68:71], v[188:191], v[44:47]
	v_mfma_f32_16x16x32_bf16 v[40:43], v[76:79], v[188:191], v[40:43]
	v_mfma_f32_16x16x32_bf16 v[28:31], v[68:71], v[214:217], v[28:31]
	v_mfma_f32_16x16x32_bf16 v[24:27], v[76:79], v[214:217], v[24:27]
	v_mfma_f32_16x16x32_bf16 v[12:15], v[68:71], v[222:225], v[12:15]
	v_mfma_f32_16x16x32_bf16 v[8:11], v[76:79], v[222:225], v[8:11]
	v_mfma_f32_16x16x32_bf16 v[52:55], v[154:157], v[176:179], v[52:55]
	v_mfma_f32_16x16x32_bf16 v[48:51], v[168:171], v[176:179], v[48:51]
	v_mfma_f32_16x16x32_bf16 v[36:39], v[154:157], v[184:187], v[36:39]
	v_mfma_f32_16x16x32_bf16 v[32:35], v[168:171], v[184:187], v[32:35]
	v_mfma_f32_16x16x32_bf16 v[20:23], v[154:157], v[210:213], v[20:23]
	v_mfma_f32_16x16x32_bf16 v[16:19], v[168:171], v[210:213], v[16:19]
	v_mfma_f32_16x16x32_bf16 v[4:7], v[154:157], v[218:221], v[4:7]
	v_mfma_f32_16x16x32_bf16 v[0:3], v[168:171], v[218:221], v[0:3]
	v_mfma_f32_16x16x32_bf16 v[52:55], v[164:167], v[180:183], v[52:55]
	v_mfma_f32_16x16x32_bf16 v[48:51], v[172:175], v[180:183], v[48:51]
	v_mfma_f32_16x16x32_bf16 v[36:39], v[164:167], v[188:191], v[36:39]
	v_mfma_f32_16x16x32_bf16 v[32:35], v[172:175], v[188:191], v[32:35]
	v_mfma_f32_16x16x32_bf16 v[20:23], v[164:167], v[214:217], v[20:23]
	v_mfma_f32_16x16x32_bf16 v[16:19], v[172:175], v[214:217], v[16:19]
	v_mfma_f32_16x16x32_bf16 v[4:7], v[164:167], v[222:225], v[4:7]
	v_mfma_f32_16x16x32_bf16 v[0:3], v[172:175], v[222:225], v[0:3]
	s_setprio 0
	s_barrier
	s_add_i32 s28, 0, 0x18000
	s_add_i32 s29, 0, 0x1c000
	v_add_u32_e32 v76, s28, v161
	v_add_u32_e32 v172, s29, v161
	ds_read_b128 v[60:63], v76
	ds_read_b128 v[68:71], v76 offset:1024
	ds_read_b128 v[72:75], v76 offset:2048
	ds_read_b128 v[76:79], v76 offset:3072
	ds_read_b128 v[154:157], v172
	ds_read_b128 v[164:167], v172 offset:1024
	ds_read_b128 v[168:171], v172 offset:2048
	ds_read_b128 v[172:175], v172 offset:3072
	s_add_u32 s26, s94, 0x80000
	s_addc_u32 s27, s95, 0
	s_mov_b32 m0, s19
	v_lshl_add_u64 v[226:227], s[26:27], 0, v[148:149]
	ds_read_b128 v[176:179], v163 offset:32768
	ds_read_b128 v[180:183], v163 offset:33792
	ds_read_b128 v[184:187], v163 offset:34816
	ds_read_b128 v[188:191], v163 offset:35840
	ds_read_b128 v[210:213], v163 offset:36864
	ds_read_b128 v[214:217], v163 offset:37888
	ds_read_b128 v[218:221], v163 offset:38912
	ds_read_b128 v[222:225], v163 offset:39936
	global_load_lds_dwordx4 v[226:227], off
	v_lshl_add_u64 v[226:227], s[26:27], 0, v[146:147]
	s_mov_b32 m0, s20
	s_nop 0
	global_load_lds_dwordx4 v[226:227], off
	s_waitcnt vmcnt(8)
	s_waitcnt lgkmcnt(0)
	s_barrier
	s_setprio 1
	s_waitcnt lgkmcnt(0)
	v_mfma_f32_16x16x32_bf16 v[140:143], v[60:63], v[176:179], v[140:143]
	v_mfma_f32_16x16x32_bf16 v[136:139], v[72:75], v[176:179], v[136:139]
	v_mfma_f32_16x16x32_bf16 v[124:127], v[60:63], v[184:187], v[124:127]
	v_mfma_f32_16x16x32_bf16 v[120:123], v[72:75], v[184:187], v[120:123]
	v_mfma_f32_16x16x32_bf16 v[108:111], v[60:63], v[210:213], v[108:111]
	v_mfma_f32_16x16x32_bf16 v[104:107], v[72:75], v[210:213], v[104:107]
	v_mfma_f32_16x16x32_bf16 v[92:95], v[60:63], v[218:221], v[92:95]
	v_mfma_f32_16x16x32_bf16 v[88:91], v[72:75], v[218:221], v[88:91]
	v_mfma_f32_16x16x32_bf16 v[140:143], v[68:71], v[180:183], v[140:143]
	v_mfma_f32_16x16x32_bf16 v[136:139], v[76:79], v[180:183], v[136:139]
	v_mfma_f32_16x16x32_bf16 v[124:127], v[68:71], v[188:191], v[124:127]
	v_mfma_f32_16x16x32_bf16 v[120:123], v[76:79], v[188:191], v[120:123]
	v_mfma_f32_16x16x32_bf16 v[108:111], v[68:71], v[214:217], v[108:111]
	v_mfma_f32_16x16x32_bf16 v[104:107], v[76:79], v[214:217], v[104:107]
	v_mfma_f32_16x16x32_bf16 v[92:95], v[68:71], v[222:225], v[92:95]
	v_mfma_f32_16x16x32_bf16 v[88:91], v[76:79], v[222:225], v[88:91]
	v_mfma_f32_16x16x32_bf16 v[132:135], v[154:157], v[176:179], v[132:135]
	v_mfma_f32_16x16x32_bf16 v[128:131], v[168:171], v[176:179], v[128:131]
	v_mfma_f32_16x16x32_bf16 v[116:119], v[154:157], v[184:187], v[116:119]
	v_mfma_f32_16x16x32_bf16 v[112:115], v[168:171], v[184:187], v[112:115]
	v_mfma_f32_16x16x32_bf16 v[100:103], v[154:157], v[210:213], v[100:103]
	v_mfma_f32_16x16x32_bf16 v[96:99], v[168:171], v[210:213], v[96:99]
	v_mfma_f32_16x16x32_bf16 v[84:87], v[154:157], v[218:221], v[84:87]
	v_mfma_f32_16x16x32_bf16 v[80:83], v[168:171], v[218:221], v[80:83]
	v_mfma_f32_16x16x32_bf16 v[132:135], v[164:167], v[180:183], v[132:135]
	v_mfma_f32_16x16x32_bf16 v[128:131], v[172:175], v[180:183], v[128:131]
	v_mfma_f32_16x16x32_bf16 v[116:119], v[164:167], v[188:191], v[116:119]
	v_mfma_f32_16x16x32_bf16 v[112:115], v[172:175], v[188:191], v[112:115]
	v_mfma_f32_16x16x32_bf16 v[100:103], v[164:167], v[214:217], v[100:103]
	v_mfma_f32_16x16x32_bf16 v[96:99], v[172:175], v[214:217], v[96:99]
	v_mfma_f32_16x16x32_bf16 v[84:87], v[164:167], v[222:225], v[84:87]
	v_mfma_f32_16x16x32_bf16 v[80:83], v[172:175], v[222:225], v[80:83]
	s_setprio 0
	s_barrier
; #define PG8_STAGE(bufoff, gbase, voff) do { _Pragma("unroll") for (int _i = 0; _i < 2; ++_i) _Pragma("unroll") for (int _r = 0; _r < PG8_NREP; ++_r) \
;         __builtin_amdgcn_global_load_lds((const unsigned*)((const char*)(gbase) + (voff)[_i]), (PG8_LAS unsigned*)(lds + (bufoff) + ldsw + _i * 8192), 16, 0, 0); } while (0)
; #define PG8_LDA(dst, b, h) do { _Pragma("unroll") for (int m = 0; m < 4; ++m) _Pragma("unroll") for (int k = 0; k < 2; ++k) { dst[m][k] = *(const PG8_LAS bf16x8*)(lds + PG8_SA(b, h) + aoff + m * 2048 + k * 1024); PG8_DUP((unsigned)(uintptr_t)(lds + PG8_SA(b, h) + aoff + m * 2048 + k * 1024)); } } while (0)
; #define PG8_MMA(ai, bj, At, Bt) do { __builtin_amdgcn_s_setprio(1); _Pragma("unroll") for (int m = 0; m < 4; ++m) _Pragma("unroll") for (int n = 0; n < 2; ++n) _Pragma("unroll") for (int k = 0; k < 2; ++k) \
;         acc[ai][bj][m][n] = __builtin_amdgcn_mfma_f32_16x16x32_bf16(Bt[n][k], At[m][k], acc[ai][bj][m][n], 0, 0, 0); __builtin_amdgcn_s_setprio(0); } while (0)
; #define PG8_WAIT_V(n) do { if ((n) == 0) asm volatile("s_waitcnt vmcnt(0)" ::: "memory"); else if ((n) == 2) asm volatile("s_waitcnt vmcnt(4)" ::: "memory"); else if ((n) == 4) asm volatile("s_waitcnt vmcnt(8)" ::: "memory"); \
;     else if ((n) == 6) asm volatile("s_waitcnt vmcnt(12)" ::: "memory"); else asm volatile("s_waitcnt vmcnt(16)" ::: "memory"); } while (0)
; #define PG8_WAIT_V(n) asm volatile("s_waitcnt vmcnt(" #n ")" ::: "memory")
; #define PG8_WAIT_L(n) asm volatile("s_waitcnt lgkmcnt(" #n ")" ::: "memory")
; #define PG8_BAR __builtin_amdgcn_s_barrier()
; #define PG8_SCHED __builtin_amdgcn_sched_barrier(0)
; template <class Epi, class Sched, bool ALIGN_EPI = false, bool SP2 = false>
; __device__ __forceinline__ void gemm_phase(PG8_LAS unsigned char* lds, const Gemm g, const Sched& S, const Epi& E) {
;     ...
;             PG8_LDA(At, 1, 1); PG8_STAGE(PG8_SB(1, 0), b3, voffB); PG8_STAGE(PG8_SB(1, 1), b3 + hstepB, voffB); PG8_STAGE(PG8_SA(1, 0), a3, voffA);
;             PG8_WAIT_V(8); PG8_WAIT_L(0); PG8_BAR; PG8_MMA(1, 0, At, B0); PG8_MMA(1, 1, At, B1); PG8_BAR; PG8_SCHED;
;     ...
;         if constexpr (ALIGN_EPI) { if (wr == 0) PG8_BAR; }
	s_add_i32 s26, s28, s16
	v_lshl_add_u64 v[158:159], v[158:159], 0, s[68:69]
	s_mov_b32 m0, s26
	ds_read_b128 v[176:179], v163 offset:49152
	ds_read_b128 v[180:183], v163 offset:50176
	ds_read_b128 v[184:187], v163 offset:51200
	ds_read_b128 v[188:191], v163 offset:52224
	ds_read_b128 v[210:213], v163 offset:53248
	ds_read_b128 v[214:217], v163 offset:54272
	ds_read_b128 v[218:221], v163 offset:55296
	ds_read_b128 v[222:225], v163 offset:56320
	global_load_lds_dwordx4 v[158:159], off
	s_add_i32 m0, s26, 0x2000
	s_add_u32 s26, s46, 0x80080
	v_lshl_add_u64 v[158:159], v[194:195], 0, s[68:69]
	s_addc_u32 s27, s47, 0
	s_add_i32 s28, s29, s16
	global_load_lds_dwordx4 v[158:159], off
	v_lshl_add_u64 v[158:159], s[26:27], 0, v[192:193]
	s_mov_b32 m0, s28
	s_nop 0
	global_load_lds_dwordx4 v[158:159], off
	v_lshl_add_u64 v[158:159], s[26:27], 0, v[144:145]
	s_add_i32 m0, s28, 0x2000
	s_nop 0
	global_load_lds_dwordx4 v[158:159], off
	v_lshl_add_u64 v[158:159], v[196:197], 0, s[68:69]
	s_mov_b32 m0, s21
	s_nop 0
	global_load_lds_dwordx4 v[158:159], off
	v_lshl_add_u64 v[158:159], v[200:201], 0, s[68:69]
	s_mov_b32 m0, s91
	s_nop 0
	global_load_lds_dwordx4 v[158:159], off
	s_waitcnt vmcnt(8)
	s_waitcnt lgkmcnt(0)
	s_barrier
	s_setprio 1
	s_waitcnt lgkmcnt(0)
	v_mfma_f32_16x16x32_bf16 v[64:67], v[60:63], v[176:179], v[64:67]
	v_mfma_f32_16x16x32_bf16 v[56:59], v[72:75], v[176:179], v[56:59]
	v_mfma_f32_16x16x32_bf16 v[44:47], v[60:63], v[184:187], v[44:47]
	v_mfma_f32_16x16x32_bf16 v[40:43], v[72:75], v[184:187], v[40:43]
	v_mfma_f32_16x16x32_bf16 v[28:31], v[60:63], v[210:213], v[28:31]
	v_mfma_f32_16x16x32_bf16 v[24:27], v[72:75], v[210:213], v[24:27]
	v_mfma_f32_16x16x32_bf16 v[12:15], v[60:63], v[218:221], v[12:15]
	v_mfma_f32_16x16x32_bf16 v[8:11], v[72:75], v[218:221], v[8:11]
	v_mfma_f32_16x16x32_bf16 v[64:67], v[68:71], v[180:183], v[64:67]
	v_mfma_f32_16x16x32_bf16 v[56:59], v[76:79], v[180:183], v[56:59]
	v_mfma_f32_16x16x32_bf16 v[44:47], v[68:71], v[188:191], v[44:47]
	v_mfma_f32_16x16x32_bf16 v[40:43], v[76:79], v[188:191], v[40:43]
	v_mfma_f32_16x16x32_bf16 v[28:31], v[68:71], v[214:217], v[28:31]
	v_mfma_f32_16x16x32_bf16 v[24:27], v[76:79], v[214:217], v[24:27]
	v_mfma_f32_16x16x32_bf16 v[12:15], v[68:71], v[222:225], v[12:15]
	v_mfma_f32_16x16x32_bf16 v[8:11], v[76:79], v[222:225], v[8:11]
	v_mfma_f32_16x16x32_bf16 v[52:55], v[154:157], v[176:179], v[52:55]
	v_mfma_f32_16x16x32_bf16 v[48:51], v[168:171], v[176:179], v[48:51]
	v_mfma_f32_16x16x32_bf16 v[36:39], v[154:157], v[184:187], v[36:39]
	v_mfma_f32_16x16x32_bf16 v[32:35], v[168:171], v[184:187], v[32:35]
	v_mfma_f32_16x16x32_bf16 v[20:23], v[154:157], v[210:213], v[20:23]
	v_mfma_f32_16x16x32_bf16 v[16:19], v[168:171], v[210:213], v[16:19]
	v_mfma_f32_16x16x32_bf16 v[4:7], v[154:157], v[218:221], v[4:7]
	v_mfma_f32_16x16x32_bf16 v[0:3], v[168:171], v[218:221], v[0:3]
	v_mfma_f32_16x16x32_bf16 v[52:55], v[164:167], v[180:183], v[52:55]
	v_mfma_f32_16x16x32_bf16 v[48:51], v[172:175], v[180:183], v[48:51]
	v_mfma_f32_16x16x32_bf16 v[36:39], v[164:167], v[188:191], v[36:39]
	v_mfma_f32_16x16x32_bf16 v[32:35], v[172:175], v[188:191], v[32:35]
	v_mfma_f32_16x16x32_bf16 v[20:23], v[164:167], v[214:217], v[20:23]
	v_mfma_f32_16x16x32_bf16 v[16:19], v[172:175], v[214:217], v[16:19]
	v_mfma_f32_16x16x32_bf16 v[4:7], v[164:167], v[222:225], v[4:7]
	v_mfma_f32_16x16x32_bf16 v[0:3], v[172:175], v[222:225], v[0:3]
	s_setprio 0
	s_barrier
	s_add_i32 s25, s25, 2
	s_add_u32 s44, s44, 0x100
	s_addc_u32 s45, s45, 0
	s_add_u32 vcc_hi, vcc_hi, 0x100
	s_addc_u32 s24, s24, 0
	s_cmp_gt_u32 s25, 29
	s_cbranch_scc0 .LBB0_156
	s_and_b64 vcc, exec, s[58:59]
	s_cbranch_vccz .LBB0_159
	s_barrier

; #define PG8_STAGE(bufoff, gbase, voff) do { _Pragma("unroll") for (int _i = 0; _i < 2; ++_i) _Pragma("unroll") for (int _r = 0; _r < PG8_NREP; ++_r) \
;         __builtin_amdgcn_global_load_lds((const unsigned*)((const char*)(gbase) + (voff)[_i]), (PG8_LAS unsigned*)(lds + (bufoff) + ldsw + _i * 8192), 16, 0, 0); } while (0)
; #define PG8_LDA(dst, b, h) do { _Pragma("unroll") for (int m = 0; m < 4; ++m) _Pragma("unroll") for (int k = 0; k < 2; ++k) { dst[m][k] = *(const PG8_LAS bf16x8*)(lds + PG8_SA(b, h) + aoff + m * 2048 + k * 1024); PG8_DUP((unsigned)(uintptr_t)(lds + PG8_SA(b, h) + aoff + m * 2048 + k * 1024)); } } while (0)
; #define PG8_LDB(dst, b, h) do { _Pragma("unroll") for (int n = 0; n < 2; ++n) _Pragma("unroll") for (int k = 0; k < 2; ++k) { dst[n][k] = *(const PG8_LAS bf16x8*)(lds + PG8_SB(b, h) + boff + n * 2048 + k * 1024); PG8_DUP((unsigned)(uintptr_t)(lds + PG8_SB(b, h) + boff + n * 2048 + k * 1024)); } } while (0)
; #define PG8_MMA(ai, bj, At, Bt) do { __builtin_amdgcn_s_setprio(1); _Pragma("unroll") for (int m = 0; m < 4; ++m) _Pragma("unroll") for (int n = 0; n < 2; ++n) _Pragma("unroll") for (int k = 0; k < 2; ++k) \
;         acc[ai][bj][m][n] = __builtin_amdgcn_mfma_f32_16x16x32_bf16(Bt[n][k], At[m][k], acc[ai][bj][m][n], 0, 0, 0); __builtin_amdgcn_s_setprio(0); } while (0)
; #define PG8_WAIT_V(n) do { if ((n) == 0) asm volatile("s_waitcnt vmcnt(0)" ::: "memory"); else if ((n) == 2) asm volatile("s_waitcnt vmcnt(4)" ::: "memory"); else if ((n) == 4) asm volatile("s_waitcnt vmcnt(8)" ::: "memory"); \
;     else if ((n) == 6) asm volatile("s_waitcnt vmcnt(12)" ::: "memory"); else asm volatile("s_waitcnt vmcnt(16)" ::: "memory"); } while (0)
; #define PG8_WAIT_V(n) asm volatile("s_waitcnt vmcnt(" #n ")" ::: "memory")
; template <class Epi, class Sched, bool ALIGN_EPI = false, bool SP2 = false>
; __device__ __forceinline__ void gemm_phase(PG8_LAS unsigned char* lds, const Gemm g, const Sched& S, const Epi& E) {
;     ...
;             PG8_LDB(B0, 0, 0); PG8_LDB(B1, 0, 1); PG8_SCHED; PG8_LDA(At, 0, 0); PG8_STAGE(PG8_SA(1, 1), a1 + hstepA, voffA);
;             PG8_WAIT_V(8); PG8_WAIT_L(0); PG8_BAR; PG8_MMA(0, 0, At, B0); PG8_MMA(0, 1, At, B1); PG8_BAR; PG8_SCHED;
;             PG8_LDA(At, 0, 1); PG8_STAGE(PG8_SB(0, 0), b2, voffB); PG8_STAGE(PG8_SB(0, 1), b2 + hstepB, voffB); PG8_STAGE(PG8_SA(0, 0), a2, voffA);
.LBB0_592:
	s_add_u32 s26, s54, 0xfffc0080
	s_addc_u32 s27, s55, -1
	s_add_i32 s28, 0, 0x10000
	s_cmp_eq_u32 s25, 12
	s_cselect_b32 s63, s47, s27
	s_cselect_b32 s62, s92, s26
	s_cselect_b32 s59, s45, s24
	s_cselect_b32 s58, s93, s94
	s_add_i32 s29, 0, 0x14000
	v_add_u32_e32 v154, s28, v143
	v_add_u32_e32 v170, s29, v143
	ds_read_b128 v[138:141], v154
	ds_read_b128 v[146:149], v154 offset:1024
	ds_read_b128 v[150:153], v154 offset:2048
	ds_read_b128 v[154:157], v154 offset:3072
	ds_read_b128 v[158:161], v170
	ds_read_b128 v[162:165], v170 offset:1024
	ds_read_b128 v[166:169], v170 offset:2048
	ds_read_b128 v[170:173], v170 offset:3072
	v_lshl_add_u64 v[190:191], s[54:55], 0, v[134:135]
	s_add_i32 m0, s17, 0xc000
	ds_read_b128 v[174:177], v145
	ds_read_b128 v[178:181], v145 offset:1024
	ds_read_b128 v[182:185], v145 offset:2048
	ds_read_b128 v[186:189], v145 offset:3072
	ds_read_b128 v[210:213], v145 offset:4096
	ds_read_b128 v[214:217], v145 offset:5120
	ds_read_b128 v[218:221], v145 offset:6144
	ds_read_b128 v[222:225], v145 offset:7168
	global_load_lds_dwordx4 v[190:191], off
	v_lshl_add_u64 v[190:191], s[54:55], 0, v[136:137]
	s_add_i32 m0, s17, 0xe000
	s_nop 0
	global_load_lds_dwordx4 v[190:191], off
	s_waitcnt vmcnt(8)
	s_waitcnt lgkmcnt(0)
	s_barrier
	s_setprio 1
	s_waitcnt lgkmcnt(0)
	v_mfma_f32_16x16x32_bf16 v[124:127], v[138:141], v[174:177], v[124:127]
	v_mfma_f32_16x16x32_bf16 v[120:123], v[150:153], v[174:177], v[120:123]
	v_mfma_f32_16x16x32_bf16 v[112:115], v[138:141], v[182:185], v[112:115]
	v_mfma_f32_16x16x32_bf16 v[104:107], v[150:153], v[182:185], v[104:107]
	v_mfma_f32_16x16x32_bf16 v[96:99], v[138:141], v[210:213], v[96:99]
	v_mfma_f32_16x16x32_bf16 v[88:91], v[150:153], v[210:213], v[88:91]
	v_mfma_f32_16x16x32_bf16 v[80:83], v[138:141], v[218:221], v[80:83]
	v_mfma_f32_16x16x32_bf16 v[72:75], v[150:153], v[218:221], v[72:75]
	v_mfma_f32_16x16x32_bf16 v[124:127], v[146:149], v[178:181], v[124:127]
	v_mfma_f32_16x16x32_bf16 v[120:123], v[154:157], v[178:181], v[120:123]
	v_mfma_f32_16x16x32_bf16 v[112:115], v[146:149], v[186:189], v[112:115]
	v_mfma_f32_16x16x32_bf16 v[104:107], v[154:157], v[186:189], v[104:107]
	v_mfma_f32_16x16x32_bf16 v[96:99], v[146:149], v[214:217], v[96:99]
	v_mfma_f32_16x16x32_bf16 v[88:91], v[154:157], v[214:217], v[88:91]
	v_mfma_f32_16x16x32_bf16 v[80:83], v[146:149], v[222:225], v[80:83]
	v_mfma_f32_16x16x32_bf16 v[72:75], v[154:157], v[222:225], v[72:75]
	v_mfma_f32_16x16x32_bf16 v[116:119], v[158:161], v[174:177], v[116:119]
	v_mfma_f32_16x16x32_bf16 v[108:111], v[166:169], v[174:177], v[108:111]
	v_mfma_f32_16x16x32_bf16 v[100:103], v[158:161], v[182:185], v[100:103]
	v_mfma_f32_16x16x32_bf16 v[92:95], v[166:169], v[182:185], v[92:95]
	v_mfma_f32_16x16x32_bf16 v[84:87], v[158:161], v[210:213], v[84:87]
	v_mfma_f32_16x16x32_bf16 v[76:79], v[166:169], v[210:213], v[76:79]
	v_mfma_f32_16x16x32_bf16 v[68:71], v[158:161], v[218:221], v[68:71]
	v_mfma_f32_16x16x32_bf16 v[64:67], v[166:169], v[218:221], v[64:67]
	v_mfma_f32_16x16x32_bf16 v[116:119], v[162:165], v[178:181], v[116:119]
	v_mfma_f32_16x16x32_bf16 v[108:111], v[170:173], v[178:181], v[108:111]
	v_mfma_f32_16x16x32_bf16 v[100:103], v[162:165], v[186:189], v[100:103]
	v_mfma_f32_16x16x32_bf16 v[92:95], v[170:173], v[186:189], v[92:95]
	v_mfma_f32_16x16x32_bf16 v[84:87], v[162:165], v[214:217], v[84:87]
	v_mfma_f32_16x16x32_bf16 v[76:79], v[170:173], v[214:217], v[76:79]
	v_mfma_f32_16x16x32_bf16 v[68:71], v[162:165], v[222:225], v[68:71]
	v_mfma_f32_16x16x32_bf16 v[64:67], v[170:173], v[222:225], v[64:67]
	s_setprio 0
	s_barrier
	s_add_i32 s26, s28, s16
	v_lshl_add_u64 v[190:191], s[58:59], 0, v[192:193]
	s_mov_b32 m0, s26
	ds_read_b128 v[174:177], v145 offset:16384
	ds_read_b128 v[178:181], v145 offset:17408
	ds_read_b128 v[182:185], v145 offset:18432
	ds_read_b128 v[186:189], v145 offset:19456
	ds_read_b128 v[210:213], v145 offset:20480
	ds_read_b128 v[214:217], v145 offset:21504
	ds_read_b128 v[218:221], v145 offset:22528
	ds_read_b128 v[222:225], v145 offset:23552
	global_load_lds_dwordx4 v[190:191], off
	s_add_i32 m0, s26, 0x2000
	s_add_u32 s26, s58, 0x40000
	v_lshl_add_u64 v[194:195], s[58:59], 0, v[128:129]
	s_addc_u32 s27, s59, 0
	s_add_i32 s28, s29, s16
	global_load_lds_dwordx4 v[194:195], off
	v_lshl_add_u64 v[196:197], s[26:27], 0, v[192:193]
	s_mov_b32 m0, s28
	v_lshl_add_u64 v[200:201], s[62:63], 0, v[130:131]
	global_load_lds_dwordx4 v[196:197], off
	v_lshl_add_u64 v[196:197], s[26:27], 0, v[128:129]
	s_add_i32 m0, s28, 0x2000
	s_nop 0
	global_load_lds_dwordx4 v[196:197], off
	v_lshl_add_u64 v[196:197], s[62:63], 0, v[132:133]
	s_mov_b32 m0, s17
	s_nop 0
	global_load_lds_dwordx4 v[196:197], off
	s_mov_b32 m0, s18
	s_nop 0
	global_load_lds_dwordx4 v[200:201], off
	s_waitcnt vmcnt(8)
	s_waitcnt lgkmcnt(0)
	s_barrier
; #define PG8_STAGE(bufoff, gbase, voff) do { _Pragma("unroll") for (int _i = 0; _i < 2; ++_i) _Pragma("unroll") for (int _r = 0; _r < PG8_NREP; ++_r) \
;         __builtin_amdgcn_global_load_lds((const unsigned*)((const char*)(gbase) + (voff)[_i]), (PG8_LAS unsigned*)(lds + (bufoff) + ldsw + _i * 8192), 16, 0, 0); } while (0)
; #define PG8_LDA(dst, b, h) do { _Pragma("unroll") for (int m = 0; m < 4; ++m) _Pragma("unroll") for (int k = 0; k < 2; ++k) { dst[m][k] = *(const PG8_LAS bf16x8*)(lds + PG8_SA(b, h) + aoff + m * 2048 + k * 1024); PG8_DUP((unsigned)(uintptr_t)(lds + PG8_SA(b, h) + aoff + m * 2048 + k * 1024)); } } while (0)
; #define PG8_LDB(dst, b, h) do { _Pragma("unroll") for (int n = 0; n < 2; ++n) _Pragma("unroll") for (int k = 0; k < 2; ++k) { dst[n][k] = *(const PG8_LAS bf16x8*)(lds + PG8_SB(b, h) + boff + n * 2048 + k * 1024); PG8_DUP((unsigned)(uintptr_t)(lds + PG8_SB(b, h) + boff + n * 2048 + k * 1024)); } } while (0)
; #define PG8_MMA(ai, bj, At, Bt) do { __builtin_amdgcn_s_setprio(1); _Pragma("unroll") for (int m = 0; m < 4; ++m) _Pragma("unroll") for (int n = 0; n < 2; ++n) _Pragma("unroll") for (int k = 0; k < 2; ++k) \
;         acc[ai][bj][m][n] = __builtin_amdgcn_mfma_f32_16x16x32_bf16(Bt[n][k], At[m][k], acc[ai][bj][m][n], 0, 0, 0); __builtin_amdgcn_s_setprio(0); } while (0)
; #define PG8_WAIT_V(n) do { if ((n) == 0) asm volatile("s_waitcnt vmcnt(0)" ::: "memory"); else if ((n) == 2) asm volatile("s_waitcnt vmcnt(4)" ::: "memory"); else if ((n) == 4) asm volatile("s_waitcnt vmcnt(8)" ::: "memory"); \
;     else if ((n) == 6) asm volatile("s_waitcnt vmcnt(12)" ::: "memory"); else asm volatile("s_waitcnt vmcnt(16)" ::: "memory"); } while (0)
; #define PG8_WAIT_V(n) asm volatile("s_waitcnt vmcnt(" #n ")" ::: "memory")
; #define PG8_BAR __builtin_amdgcn_s_barrier()
; template <class Epi, class Sched, bool ALIGN_EPI = false, bool SP2 = false>
; __device__ __forceinline__ void gemm_phase(PG8_LAS unsigned char* lds, const Gemm g, const Sched& S, const Epi& E) {
;     ...
;             PG8_WAIT_V(8); PG8_WAIT_L(0); PG8_BAR; PG8_MMA(1, 0, At, B0); PG8_MMA(1, 1, At, B1); PG8_BAR; PG8_SCHED;
;             PG8_LDB(B0, 1, 0); PG8_LDB(B1, 1, 1); PG8_SCHED; PG8_LDA(At, 1, 0); PG8_STAGE(PG8_SA(0, 1), a2 + hstepA, voffA);
;             PG8_WAIT_V(8); PG8_WAIT_L(0); PG8_BAR; PG8_MMA(0, 0, At, B0); PG8_MMA(0, 1, At, B1); PG8_BAR; PG8_SCHED;
	s_setprio 1
	s_waitcnt lgkmcnt(0)
	v_mfma_f32_16x16x32_bf16 v[60:63], v[138:141], v[174:177], v[60:63]
	v_mfma_f32_16x16x32_bf16 v[56:59], v[150:153], v[174:177], v[56:59]
	v_mfma_f32_16x16x32_bf16 v[48:51], v[138:141], v[182:185], v[48:51]
	v_mfma_f32_16x16x32_bf16 v[40:43], v[150:153], v[182:185], v[40:43]
	v_mfma_f32_16x16x32_bf16 v[32:35], v[138:141], v[210:213], v[32:35]
	v_mfma_f32_16x16x32_bf16 v[24:27], v[150:153], v[210:213], v[24:27]
	v_mfma_f32_16x16x32_bf16 v[16:19], v[138:141], v[218:221], v[16:19]
	v_mfma_f32_16x16x32_bf16 v[8:11], v[150:153], v[218:221], v[8:11]
	v_mfma_f32_16x16x32_bf16 v[60:63], v[146:149], v[178:181], v[60:63]
	v_mfma_f32_16x16x32_bf16 v[56:59], v[154:157], v[178:181], v[56:59]
	v_mfma_f32_16x16x32_bf16 v[48:51], v[146:149], v[186:189], v[48:51]
	v_mfma_f32_16x16x32_bf16 v[40:43], v[154:157], v[186:189], v[40:43]
	v_mfma_f32_16x16x32_bf16 v[32:35], v[146:149], v[214:217], v[32:35]
	v_mfma_f32_16x16x32_bf16 v[24:27], v[154:157], v[214:217], v[24:27]
	v_mfma_f32_16x16x32_bf16 v[16:19], v[146:149], v[222:225], v[16:19]
	v_mfma_f32_16x16x32_bf16 v[8:11], v[154:157], v[222:225], v[8:11]
	v_mfma_f32_16x16x32_bf16 v[52:55], v[158:161], v[174:177], v[52:55]
	v_mfma_f32_16x16x32_bf16 v[44:47], v[166:169], v[174:177], v[44:47]
	v_mfma_f32_16x16x32_bf16 v[36:39], v[158:161], v[182:185], v[36:39]
	v_mfma_f32_16x16x32_bf16 v[28:31], v[166:169], v[182:185], v[28:31]
	v_mfma_f32_16x16x32_bf16 v[20:23], v[158:161], v[210:213], v[20:23]
	v_mfma_f32_16x16x32_bf16 v[12:15], v[166:169], v[210:213], v[12:15]
	v_mfma_f32_16x16x32_bf16 v[4:7], v[158:161], v[218:221], v[4:7]
	v_mfma_f32_16x16x32_bf16 v[0:3], v[166:169], v[218:221], v[0:3]
	v_mfma_f32_16x16x32_bf16 v[52:55], v[162:165], v[178:181], v[52:55]
	v_mfma_f32_16x16x32_bf16 v[44:47], v[170:173], v[178:181], v[44:47]
	v_mfma_f32_16x16x32_bf16 v[36:39], v[162:165], v[186:189], v[36:39]
	v_mfma_f32_16x16x32_bf16 v[28:31], v[170:173], v[186:189], v[28:31]
	v_mfma_f32_16x16x32_bf16 v[20:23], v[162:165], v[214:217], v[20:23]
	v_mfma_f32_16x16x32_bf16 v[12:15], v[170:173], v[214:217], v[12:15]
	v_mfma_f32_16x16x32_bf16 v[4:7], v[162:165], v[222:225], v[4:7]
	v_mfma_f32_16x16x32_bf16 v[0:3], v[170:173], v[222:225], v[0:3]
	s_setprio 0
	s_barrier
	s_add_i32 s28, 0, 0x18000
	s_add_i32 s29, 0, 0x1c000
	v_add_u32_e32 v154, s28, v143
	v_add_u32_e32 v170, s29, v143
	ds_read_b128 v[138:141], v154
	ds_read_b128 v[146:149], v154 offset:1024
	ds_read_b128 v[150:153], v154 offset:2048
	ds_read_b128 v[154:157], v154 offset:3072
	ds_read_b128 v[158:161], v170
	ds_read_b128 v[162:165], v170 offset:1024
	ds_read_b128 v[166:169], v170 offset:2048
	ds_read_b128 v[170:173], v170 offset:3072
	s_add_u32 s26, s62, 0x40000
	s_addc_u32 s27, s63, 0
	s_mov_b32 m0, s19
	v_lshl_add_u64 v[226:227], s[26:27], 0, v[132:133]
	ds_read_b128 v[174:177], v145 offset:32768
	ds_read_b128 v[178:181], v145 offset:33792
	ds_read_b128 v[182:185], v145 offset:34816
	ds_read_b128 v[186:189], v145 offset:35840
	ds_read_b128 v[210:213], v145 offset:36864
	ds_read_b128 v[214:217], v145 offset:37888
	ds_read_b128 v[218:221], v145 offset:38912
	ds_read_b128 v[222:225], v145 offset:39936
	global_load_lds_dwordx4 v[226:227], off
	v_lshl_add_u64 v[226:227], s[26:27], 0, v[130:131]
	s_mov_b32 m0, s20
	s_nop 0
	global_load_lds_dwordx4 v[226:227], off
	s_waitcnt vmcnt(8)
	s_waitcnt lgkmcnt(0)
	s_barrier
	s_setprio 1
	s_waitcnt lgkmcnt(0)
	v_mfma_f32_16x16x32_bf16 v[124:127], v[138:141], v[174:177], v[124:127]
	v_mfma_f32_16x16x32_bf16 v[120:123], v[150:153], v[174:177], v[120:123]
	v_mfma_f32_16x16x32_bf16 v[112:115], v[138:141], v[182:185], v[112:115]
	v_mfma_f32_16x16x32_bf16 v[104:107], v[150:153], v[182:185], v[104:107]
	v_mfma_f32_16x16x32_bf16 v[96:99], v[138:141], v[210:213], v[96:99]
	v_mfma_f32_16x16x32_bf16 v[88:91], v[150:153], v[210:213], v[88:91]
	v_mfma_f32_16x16x32_bf16 v[80:83], v[138:141], v[218:221], v[80:83]
	v_mfma_f32_16x16x32_bf16 v[72:75], v[150:153], v[218:221], v[72:75]
	v_mfma_f32_16x16x32_bf16 v[124:127], v[146:149], v[178:181], v[124:127]
	v_mfma_f32_16x16x32_bf16 v[120:123], v[154:157], v[178:181], v[120:123]
	v_mfma_f32_16x16x32_bf16 v[112:115], v[146:149], v[186:189], v[112:115]
	v_mfma_f32_16x16x32_bf16 v[104:107], v[154:157], v[186:189], v[104:107]
	v_mfma_f32_16x16x32_bf16 v[96:99], v[146:149], v[214:217], v[96:99]
	v_mfma_f32_16x16x32_bf16 v[88:91], v[154:157], v[214:217], v[88:91]
	v_mfma_f32_16x16x32_bf16 v[80:83], v[146:149], v[222:225], v[80:83]
	v_mfma_f32_16x16x32_bf16 v[72:75], v[154:157], v[222:225], v[72:75]
	v_mfma_f32_16x16x32_bf16 v[116:119], v[158:161], v[174:177], v[116:119]
	v_mfma_f32_16x16x32_bf16 v[108:111], v[166:169], v[174:177], v[108:111]
	v_mfma_f32_16x16x32_bf16 v[100:103], v[158:161], v[182:185], v[100:103]
	v_mfma_f32_16x16x32_bf16 v[92:95], v[166:169], v[182:185], v[92:95]
	v_mfma_f32_16x16x32_bf16 v[84:87], v[158:161], v[210:213], v[84:87]
	v_mfma_f32_16x16x32_bf16 v[76:79], v[166:169], v[210:213], v[76:79]
	v_mfma_f32_16x16x32_bf16 v[68:71], v[158:161], v[218:221], v[68:71]
	v_mfma_f32_16x16x32_bf16 v[64:67], v[166:169], v[218:221], v[64:67]
	v_mfma_f32_16x16x32_bf16 v[116:119], v[162:165], v[178:181], v[116:119]
	v_mfma_f32_16x16x32_bf16 v[108:111], v[170:173], v[178:181], v[108:111]
	v_mfma_f32_16x16x32_bf16 v[100:103], v[162:165], v[186:189], v[100:103]
	v_mfma_f32_16x16x32_bf16 v[92:95], v[170:173], v[186:189], v[92:95]
	v_mfma_f32_16x16x32_bf16 v[84:87], v[162:165], v[214:217], v[84:87]
	v_mfma_f32_16x16x32_bf16 v[76:79], v[170:173], v[214:217], v[76:79]
	v_mfma_f32_16x16x32_bf16 v[68:71], v[162:165], v[222:225], v[68:71]
	v_mfma_f32_16x16x32_bf16 v[64:67], v[170:173], v[222:225], v[64:67]
	s_setprio 0
	s_barrier
; #define PG8_STAGE(bufoff, gbase, voff) do { _Pragma("unroll") for (int _i = 0; _i < 2; ++_i) _Pragma("unroll") for (int _r = 0; _r < PG8_NREP; ++_r) \
;         __builtin_amdgcn_global_load_lds((const unsigned*)((const char*)(gbase) + (voff)[_i]), (PG8_LAS unsigned*)(lds + (bufoff) + ldsw + _i * 8192), 16, 0, 0); } while (0)
; #define PG8_LDA(dst, b, h) do { _Pragma("unroll") for (int m = 0; m < 4; ++m) _Pragma("unroll") for (int k = 0; k < 2; ++k) { dst[m][k] = *(const PG8_LAS bf16x8*)(lds + PG8_SA(b, h) + aoff + m * 2048 + k * 1024); PG8_DUP((unsigned)(uintptr_t)(lds + PG8_SA(b, h) + aoff + m * 2048 + k * 1024)); } } while (0)
; #define PG8_MMA(ai, bj, At, Bt) do { __builtin_amdgcn_s_setprio(1); _Pragma("unroll") for (int m = 0; m < 4; ++m) _Pragma("unroll") for (int n = 0; n < 2; ++n) _Pragma("unroll") for (int k = 0; k < 2; ++k) \
;         acc[ai][bj][m][n] = __builtin_amdgcn_mfma_f32_16x16x32_bf16(Bt[n][k], At[m][k], acc[ai][bj][m][n], 0, 0, 0); __builtin_amdgcn_s_setprio(0); } while (0)
; #define PG8_WAIT_V(n) do { if ((n) == 0) asm volatile("s_waitcnt vmcnt(0)" ::: "memory"); else if ((n) == 2) asm volatile("s_waitcnt vmcnt(4)" ::: "memory"); else if ((n) == 4) asm volatile("s_waitcnt vmcnt(8)" ::: "memory"); \
;     else if ((n) == 6) asm volatile("s_waitcnt vmcnt(12)" ::: "memory"); else asm volatile("s_waitcnt vmcnt(16)" ::: "memory"); } while (0)
; #define PG8_WAIT_V(n) asm volatile("s_waitcnt vmcnt(" #n ")" ::: "memory")
; #define PG8_WAIT_L(n) asm volatile("s_waitcnt lgkmcnt(" #n ")" ::: "memory")
; #define PG8_BAR __builtin_amdgcn_s_barrier()
; #define PG8_SCHED __builtin_amdgcn_sched_barrier(0)
; template <class Epi, class Sched, bool ALIGN_EPI = false, bool SP2 = false>
; __device__ __forceinline__ void gemm_phase(PG8_LAS unsigned char* lds, const Gemm g, const Sched& S, const Epi& E) {
;     ...
;             PG8_LDA(At, 1, 1); PG8_STAGE(PG8_SB(1, 0), b3, voffB); PG8_STAGE(PG8_SB(1, 1), b3 + hstepB, voffB); PG8_STAGE(PG8_SA(1, 0), a3, voffA);
;             PG8_WAIT_V(8); PG8_WAIT_L(0); PG8_BAR; PG8_MMA(1, 0, At, B0); PG8_MMA(1, 1, At, B1); PG8_BAR; PG8_SCHED;
;     ...
;         if constexpr (ALIGN_EPI) { if (wr == 0) PG8_BAR; }
	s_add_i32 s26, s28, s16
	v_lshl_add_u64 v[190:191], v[190:191], 0, s[68:69]
	s_mov_b32 m0, s26
	ds_read_b128 v[174:177], v145 offset:49152
	ds_read_b128 v[178:181], v145 offset:50176
	ds_read_b128 v[182:185], v145 offset:51200
	ds_read_b128 v[186:189], v145 offset:52224
	ds_read_b128 v[210:213], v145 offset:53248
	ds_read_b128 v[214:217], v145 offset:54272
	ds_read_b128 v[218:221], v145 offset:55296
	ds_read_b128 v[222:225], v145 offset:56320
	global_load_lds_dwordx4 v[190:191], off
	s_add_i32 m0, s26, 0x2000
	s_add_u32 s26, s58, 0x40080
	v_lshl_add_u64 v[190:191], v[194:195], 0, s[68:69]
	s_addc_u32 s27, s59, 0
	s_add_i32 s28, s29, s16
	global_load_lds_dwordx4 v[190:191], off
	v_lshl_add_u64 v[190:191], s[26:27], 0, v[192:193]
	s_mov_b32 m0, s28
	s_nop 0
	global_load_lds_dwordx4 v[190:191], off
	v_lshl_add_u64 v[190:191], s[26:27], 0, v[128:129]
	s_add_i32 m0, s28, 0x2000
	s_nop 0
	global_load_lds_dwordx4 v[190:191], off
	v_lshl_add_u64 v[190:191], v[196:197], 0, s[68:69]
	s_mov_b32 m0, s21
	s_nop 0
	global_load_lds_dwordx4 v[190:191], off
	v_lshl_add_u64 v[190:191], v[200:201], 0, s[68:69]
	s_mov_b32 m0, s22
	s_nop 0
	global_load_lds_dwordx4 v[190:191], off
	s_waitcnt vmcnt(8)
	s_waitcnt lgkmcnt(0)
	s_barrier
	s_setprio 1
	s_waitcnt lgkmcnt(0)
	v_mfma_f32_16x16x32_bf16 v[60:63], v[138:141], v[174:177], v[60:63]
	v_mfma_f32_16x16x32_bf16 v[56:59], v[150:153], v[174:177], v[56:59]
	v_mfma_f32_16x16x32_bf16 v[48:51], v[138:141], v[182:185], v[48:51]
	v_mfma_f32_16x16x32_bf16 v[40:43], v[150:153], v[182:185], v[40:43]
	v_mfma_f32_16x16x32_bf16 v[32:35], v[138:141], v[210:213], v[32:35]
	v_mfma_f32_16x16x32_bf16 v[24:27], v[150:153], v[210:213], v[24:27]
	v_mfma_f32_16x16x32_bf16 v[16:19], v[138:141], v[218:221], v[16:19]
	v_mfma_f32_16x16x32_bf16 v[8:11], v[150:153], v[218:221], v[8:11]
	v_mfma_f32_16x16x32_bf16 v[60:63], v[146:149], v[178:181], v[60:63]
	v_mfma_f32_16x16x32_bf16 v[56:59], v[154:157], v[178:181], v[56:59]
	v_mfma_f32_16x16x32_bf16 v[48:51], v[146:149], v[186:189], v[48:51]
	v_mfma_f32_16x16x32_bf16 v[40:43], v[154:157], v[186:189], v[40:43]
	v_mfma_f32_16x16x32_bf16 v[32:35], v[146:149], v[214:217], v[32:35]
	v_mfma_f32_16x16x32_bf16 v[24:27], v[154:157], v[214:217], v[24:27]
	v_mfma_f32_16x16x32_bf16 v[16:19], v[146:149], v[222:225], v[16:19]
	v_mfma_f32_16x16x32_bf16 v[8:11], v[154:157], v[222:225], v[8:11]
	v_mfma_f32_16x16x32_bf16 v[52:55], v[158:161], v[174:177], v[52:55]
	v_mfma_f32_16x16x32_bf16 v[44:47], v[166:169], v[174:177], v[44:47]
	v_mfma_f32_16x16x32_bf16 v[36:39], v[158:161], v[182:185], v[36:39]
	v_mfma_f32_16x16x32_bf16 v[28:31], v[166:169], v[182:185], v[28:31]
	v_mfma_f32_16x16x32_bf16 v[20:23], v[158:161], v[210:213], v[20:23]
	v_mfma_f32_16x16x32_bf16 v[12:15], v[166:169], v[210:213], v[12:15]
	v_mfma_f32_16x16x32_bf16 v[4:7], v[158:161], v[218:221], v[4:7]
	v_mfma_f32_16x16x32_bf16 v[0:3], v[166:169], v[218:221], v[0:3]
	v_mfma_f32_16x16x32_bf16 v[52:55], v[162:165], v[178:181], v[52:55]
	v_mfma_f32_16x16x32_bf16 v[44:47], v[170:173], v[178:181], v[44:47]
	v_mfma_f32_16x16x32_bf16 v[36:39], v[162:165], v[186:189], v[36:39]
	v_mfma_f32_16x16x32_bf16 v[28:31], v[170:173], v[186:189], v[28:31]
	v_mfma_f32_16x16x32_bf16 v[20:23], v[162:165], v[214:217], v[20:23]
	v_mfma_f32_16x16x32_bf16 v[12:15], v[170:173], v[214:217], v[12:15]
	v_mfma_f32_16x16x32_bf16 v[4:7], v[162:165], v[222:225], v[4:7]
	v_mfma_f32_16x16x32_bf16 v[0:3], v[170:173], v[222:225], v[0:3]
	s_setprio 0
	s_barrier
	s_add_i32 s25, s25, 2
	s_add_u32 s54, s54, 0x100
	s_addc_u32 s55, s55, 0
	s_add_u32 s94, s94, 0x100
	s_addc_u32 s24, s24, 0
	s_cmp_gt_u32 s25, 13
	s_cbranch_scc0 .LBB0_592
	s_and_b64 vcc, exec, s[40:41]
	s_cbranch_vccz .LBB0_595
	s_barrier

; #define PG8_STAGE(bufoff, gbase, voff) do { _Pragma("unroll") for (int _i = 0; _i < 2; ++_i) _Pragma("unroll") for (int _r = 0; _r < PG8_NREP; ++_r) \
;         __builtin_amdgcn_global_load_lds((const unsigned*)((const char*)(gbase) + (voff)[_i]), (PG8_LAS unsigned*)(lds + (bufoff) + ldsw + _i * 8192), 16, 0, 0); } while (0)
; #define PG8_LDA(dst, b, h) do { _Pragma("unroll") for (int m = 0; m < 4; ++m) _Pragma("unroll") for (int k = 0; k < 2; ++k) { dst[m][k] = *(const PG8_LAS bf16x8*)(lds + PG8_SA(b, h) + aoff + m * 2048 + k * 1024); PG8_DUP((unsigned)(uintptr_t)(lds + PG8_SA(b, h) + aoff + m * 2048 + k * 1024)); } } while (0)
; #define PG8_LDB(dst, b, h) do { _Pragma("unroll") for (int n = 0; n < 2; ++n) _Pragma("unroll") for (int k = 0; k < 2; ++k) { dst[n][k] = *(const PG8_LAS bf16x8*)(lds + PG8_SB(b, h) + boff + n * 2048 + k * 1024); PG8_DUP((unsigned)(uintptr_t)(lds + PG8_SB(b, h) + boff + n * 2048 + k * 1024)); } } while (0)
; #define PG8_MMA(ai, bj, At, Bt) do { __builtin_amdgcn_s_setprio(1); _Pragma("unroll") for (int m = 0; m < 4; ++m) _Pragma("unroll") for (int n = 0; n < 2; ++n) _Pragma("unroll") for (int k = 0; k < 2; ++k) \
;         acc[ai][bj][m][n] = __builtin_amdgcn_mfma_f32_16x16x32_bf16(Bt[n][k], At[m][k], acc[ai][bj][m][n], 0, 0, 0); __builtin_amdgcn_s_setprio(0); } while (0)
; #define PG8_WAIT_V(n) do { if ((n) == 0) asm volatile("s_waitcnt vmcnt(0)" ::: "memory"); else if ((n) == 2) asm volatile("s_waitcnt vmcnt(4)" ::: "memory"); else if ((n) == 4) asm volatile("s_waitcnt vmcnt(8)" ::: "memory"); \
;     else if ((n) == 6) asm volatile("s_waitcnt vmcnt(12)" ::: "memory"); else asm volatile("s_waitcnt vmcnt(16)" ::: "memory"); } while (0)
; #define PG8_WAIT_V(n) asm volatile("s_waitcnt vmcnt(" #n ")" ::: "memory")
; template <class Epi, class Sched, bool ALIGN_EPI = false, bool SP2 = false>
; __device__ __forceinline__ void gemm_phase(PG8_LAS unsigned char* lds, const Gemm g, const Sched& S, const Epi& E) {
;     ...
;             PG8_LDB(B0, 0, 0); PG8_LDB(B1, 0, 1); PG8_SCHED; PG8_LDA(At, 0, 0); PG8_STAGE(PG8_SA(1, 1), a1 + hstepA, voffA);
;             PG8_WAIT_V(8); PG8_WAIT_L(0); PG8_BAR; PG8_MMA(0, 0, At, B0); PG8_MMA(0, 1, At, B1); PG8_BAR; PG8_SCHED;
;             PG8_LDA(At, 0, 1); PG8_STAGE(PG8_SB(0, 0), b2, voffB); PG8_STAGE(PG8_SB(0, 1), b2 + hstepB, voffB); PG8_STAGE(PG8_SA(0, 0), a2, voffA);
.LBB0_612:
	s_add_u32 s26, s54, 0xfffc0080
	s_addc_u32 s27, s55, -1
	s_add_i32 s28, 0, 0x10000
	s_cmp_eq_u32 s25, 12
	s_cselect_b32 s63, s47, s27
	s_cselect_b32 s62, s92, s26
	s_cselect_b32 s59, s45, s24
	s_cselect_b32 s58, s93, s94
	s_add_i32 s29, 0, 0x14000
	v_add_u32_e32 v154, s28, v147
	v_add_u32_e32 v170, s29, v147
	ds_read_b128 v[138:141], v154
	ds_read_b128 v[142:145], v154 offset:1024
	ds_read_b128 v[150:153], v154 offset:2048
	ds_read_b128 v[154:157], v154 offset:3072
	ds_read_b128 v[158:161], v170
	ds_read_b128 v[162:165], v170 offset:1024
	ds_read_b128 v[166:169], v170 offset:2048
	ds_read_b128 v[170:173], v170 offset:3072
	v_lshl_add_u64 v[190:191], s[54:55], 0, v[134:135]
	s_add_i32 m0, s17, 0xc000
	ds_read_b128 v[174:177], v149
	ds_read_b128 v[178:181], v149 offset:1024
	ds_read_b128 v[182:185], v149 offset:2048
	ds_read_b128 v[186:189], v149 offset:3072
	ds_read_b128 v[210:213], v149 offset:4096
	ds_read_b128 v[214:217], v149 offset:5120
	ds_read_b128 v[218:221], v149 offset:6144
	ds_read_b128 v[222:225], v149 offset:7168
	global_load_lds_dwordx4 v[190:191], off
	v_lshl_add_u64 v[190:191], s[54:55], 0, v[136:137]
	s_add_i32 m0, s17, 0xe000
	s_nop 0
	global_load_lds_dwordx4 v[190:191], off
	s_waitcnt vmcnt(8)
	s_waitcnt lgkmcnt(0)
	s_barrier
	s_setprio 1
	s_waitcnt lgkmcnt(0)
	v_mfma_f32_16x16x32_bf16 v[124:127], v[138:141], v[174:177], v[124:127]
	v_mfma_f32_16x16x32_bf16 v[120:123], v[150:153], v[174:177], v[120:123]
	v_mfma_f32_16x16x32_bf16 v[108:111], v[138:141], v[182:185], v[108:111]
	v_mfma_f32_16x16x32_bf16 v[104:107], v[150:153], v[182:185], v[104:107]
	v_mfma_f32_16x16x32_bf16 v[92:95], v[138:141], v[210:213], v[92:95]
	v_mfma_f32_16x16x32_bf16 v[88:91], v[150:153], v[210:213], v[88:91]
	v_mfma_f32_16x16x32_bf16 v[76:79], v[138:141], v[218:221], v[76:79]
	v_mfma_f32_16x16x32_bf16 v[72:75], v[150:153], v[218:221], v[72:75]
	v_mfma_f32_16x16x32_bf16 v[124:127], v[142:145], v[178:181], v[124:127]
	v_mfma_f32_16x16x32_bf16 v[120:123], v[154:157], v[178:181], v[120:123]
	v_mfma_f32_16x16x32_bf16 v[108:111], v[142:145], v[186:189], v[108:111]
	v_mfma_f32_16x16x32_bf16 v[104:107], v[154:157], v[186:189], v[104:107]
	v_mfma_f32_16x16x32_bf16 v[92:95], v[142:145], v[214:217], v[92:95]
	v_mfma_f32_16x16x32_bf16 v[88:91], v[154:157], v[214:217], v[88:91]
	v_mfma_f32_16x16x32_bf16 v[76:79], v[142:145], v[222:225], v[76:79]
	v_mfma_f32_16x16x32_bf16 v[72:75], v[154:157], v[222:225], v[72:75]
	v_mfma_f32_16x16x32_bf16 v[116:119], v[158:161], v[174:177], v[116:119]
	v_mfma_f32_16x16x32_bf16 v[112:115], v[166:169], v[174:177], v[112:115]
	v_mfma_f32_16x16x32_bf16 v[100:103], v[158:161], v[182:185], v[100:103]
	v_mfma_f32_16x16x32_bf16 v[96:99], v[166:169], v[182:185], v[96:99]
	v_mfma_f32_16x16x32_bf16 v[84:87], v[158:161], v[210:213], v[84:87]
	v_mfma_f32_16x16x32_bf16 v[80:83], v[166:169], v[210:213], v[80:83]
	v_mfma_f32_16x16x32_bf16 v[68:71], v[158:161], v[218:221], v[68:71]
	v_mfma_f32_16x16x32_bf16 v[64:67], v[166:169], v[218:221], v[64:67]
	v_mfma_f32_16x16x32_bf16 v[116:119], v[162:165], v[178:181], v[116:119]
	v_mfma_f32_16x16x32_bf16 v[112:115], v[170:173], v[178:181], v[112:115]
	v_mfma_f32_16x16x32_bf16 v[100:103], v[162:165], v[186:189], v[100:103]
	v_mfma_f32_16x16x32_bf16 v[96:99], v[170:173], v[186:189], v[96:99]
	v_mfma_f32_16x16x32_bf16 v[84:87], v[162:165], v[214:217], v[84:87]
	v_mfma_f32_16x16x32_bf16 v[80:83], v[170:173], v[214:217], v[80:83]
	v_mfma_f32_16x16x32_bf16 v[68:71], v[162:165], v[222:225], v[68:71]
	v_mfma_f32_16x16x32_bf16 v[64:67], v[170:173], v[222:225], v[64:67]
	s_setprio 0
	s_barrier
	s_add_i32 s26, s28, s16
	v_lshl_add_u64 v[190:191], s[58:59], 0, v[192:193]
	s_mov_b32 m0, s26
	ds_read_b128 v[174:177], v149 offset:16384
	ds_read_b128 v[178:181], v149 offset:17408
	ds_read_b128 v[182:185], v149 offset:18432
	ds_read_b128 v[186:189], v149 offset:19456
	ds_read_b128 v[210:213], v149 offset:20480
	ds_read_b128 v[214:217], v149 offset:21504
	ds_read_b128 v[218:221], v149 offset:22528
	ds_read_b128 v[222:225], v149 offset:23552
	global_load_lds_dwordx4 v[190:191], off
	s_add_i32 m0, s26, 0x2000
	s_add_u32 s26, s58, 0x40000
	v_lshl_add_u64 v[194:195], s[58:59], 0, v[128:129]
	s_addc_u32 s27, s59, 0
	s_add_i32 s28, s29, s16
	global_load_lds_dwordx4 v[194:195], off
	v_lshl_add_u64 v[196:197], s[26:27], 0, v[192:193]
	s_mov_b32 m0, s28
	v_lshl_add_u64 v[200:201], s[62:63], 0, v[130:131]
	global_load_lds_dwordx4 v[196:197], off
	v_lshl_add_u64 v[196:197], s[26:27], 0, v[128:129]
	s_add_i32 m0, s28, 0x2000
	s_nop 0
	global_load_lds_dwordx4 v[196:197], off
	v_lshl_add_u64 v[196:197], s[62:63], 0, v[132:133]
	s_mov_b32 m0, s17
	s_nop 0
	global_load_lds_dwordx4 v[196:197], off
	s_mov_b32 m0, s18
	s_nop 0
	global_load_lds_dwordx4 v[200:201], off
	s_waitcnt vmcnt(8)
	s_waitcnt lgkmcnt(0)
	s_barrier
; #define PG8_STAGE(bufoff, gbase, voff) do { _Pragma("unroll") for (int _i = 0; _i < 2; ++_i) _Pragma("unroll") for (int _r = 0; _r < PG8_NREP; ++_r) \
;         __builtin_amdgcn_global_load_lds((const unsigned*)((const char*)(gbase) + (voff)[_i]), (PG8_LAS unsigned*)(lds + (bufoff) + ldsw + _i * 8192), 16, 0, 0); } while (0)
; #define PG8_LDA(dst, b, h) do { _Pragma("unroll") for (int m = 0; m < 4; ++m) _Pragma("unroll") for (int k = 0; k < 2; ++k) { dst[m][k] = *(const PG8_LAS bf16x8*)(lds + PG8_SA(b, h) + aoff + m * 2048 + k * 1024); PG8_DUP((unsigned)(uintptr_t)(lds + PG8_SA(b, h) + aoff + m * 2048 + k * 1024)); } } while (0)
; #define PG8_LDB(dst, b, h) do { _Pragma("unroll") for (int n = 0; n < 2; ++n) _Pragma("unroll") for (int k = 0; k < 2; ++k) { dst[n][k] = *(const PG8_LAS bf16x8*)(lds + PG8_SB(b, h) + boff + n * 2048 + k * 1024); PG8_DUP((unsigned)(uintptr_t)(lds + PG8_SB(b, h) + boff + n * 2048 + k * 1024)); } } while (0)
; #define PG8_MMA(ai, bj, At, Bt) do { __builtin_amdgcn_s_setprio(1); _Pragma("unroll") for (int m = 0; m < 4; ++m) _Pragma("unroll") for (int n = 0; n < 2; ++n) _Pragma("unroll") for (int k = 0; k < 2; ++k) \
;         acc[ai][bj][m][n] = __builtin_amdgcn_mfma_f32_16x16x32_bf16(Bt[n][k], At[m][k], acc[ai][bj][m][n], 0, 0, 0); __builtin_amdgcn_s_setprio(0); } while (0)
; #define PG8_WAIT_V(n) do { if ((n) == 0) asm volatile("s_waitcnt vmcnt(0)" ::: "memory"); else if ((n) == 2) asm volatile("s_waitcnt vmcnt(4)" ::: "memory"); else if ((n) == 4) asm volatile("s_waitcnt vmcnt(8)" ::: "memory"); \
;     else if ((n) == 6) asm volatile("s_waitcnt vmcnt(12)" ::: "memory"); else asm volatile("s_waitcnt vmcnt(16)" ::: "memory"); } while (0)
; #define PG8_WAIT_V(n) asm volatile("s_waitcnt vmcnt(" #n ")" ::: "memory")
; #define PG8_BAR __builtin_amdgcn_s_barrier()
; template <class Epi, class Sched, bool ALIGN_EPI = false, bool SP2 = false>
; __device__ __forceinline__ void gemm_phase(PG8_LAS unsigned char* lds, const Gemm g, const Sched& S, const Epi& E) {
;     ...
;             PG8_WAIT_V(8); PG8_WAIT_L(0); PG8_BAR; PG8_MMA(1, 0, At, B0); PG8_MMA(1, 1, At, B1); PG8_BAR; PG8_SCHED;
;             PG8_LDB(B0, 1, 0); PG8_LDB(B1, 1, 1); PG8_SCHED; PG8_LDA(At, 1, 0); PG8_STAGE(PG8_SA(0, 1), a2 + hstepA, voffA);
;             PG8_WAIT_V(8); PG8_WAIT_L(0); PG8_BAR; PG8_MMA(0, 0, At, B0); PG8_MMA(0, 1, At, B1); PG8_BAR; PG8_SCHED;
	s_setprio 1
	s_waitcnt lgkmcnt(0)
	v_mfma_f32_16x16x32_bf16 v[60:63], v[138:141], v[174:177], v[60:63]
	v_mfma_f32_16x16x32_bf16 v[56:59], v[150:153], v[174:177], v[56:59]
	v_mfma_f32_16x16x32_bf16 v[44:47], v[138:141], v[182:185], v[44:47]
	v_mfma_f32_16x16x32_bf16 v[40:43], v[150:153], v[182:185], v[40:43]
	v_mfma_f32_16x16x32_bf16 v[28:31], v[138:141], v[210:213], v[28:31]
	v_mfma_f32_16x16x32_bf16 v[24:27], v[150:153], v[210:213], v[24:27]
	v_mfma_f32_16x16x32_bf16 v[12:15], v[138:141], v[218:221], v[12:15]
	v_mfma_f32_16x16x32_bf16 v[8:11], v[150:153], v[218:221], v[8:11]
	v_mfma_f32_16x16x32_bf16 v[60:63], v[142:145], v[178:181], v[60:63]
	v_mfma_f32_16x16x32_bf16 v[56:59], v[154:157], v[178:181], v[56:59]
	v_mfma_f32_16x16x32_bf16 v[44:47], v[142:145], v[186:189], v[44:47]
	v_mfma_f32_16x16x32_bf16 v[40:43], v[154:157], v[186:189], v[40:43]
	v_mfma_f32_16x16x32_bf16 v[28:31], v[142:145], v[214:217], v[28:31]
	v_mfma_f32_16x16x32_bf16 v[24:27], v[154:157], v[214:217], v[24:27]
	v_mfma_f32_16x16x32_bf16 v[12:15], v[142:145], v[222:225], v[12:15]
	v_mfma_f32_16x16x32_bf16 v[8:11], v[154:157], v[222:225], v[8:11]
	v_mfma_f32_16x16x32_bf16 v[52:55], v[158:161], v[174:177], v[52:55]
	v_mfma_f32_16x16x32_bf16 v[48:51], v[166:169], v[174:177], v[48:51]
	v_mfma_f32_16x16x32_bf16 v[36:39], v[158:161], v[182:185], v[36:39]
	v_mfma_f32_16x16x32_bf16 v[32:35], v[166:169], v[182:185], v[32:35]
	v_mfma_f32_16x16x32_bf16 v[20:23], v[158:161], v[210:213], v[20:23]
	v_mfma_f32_16x16x32_bf16 v[16:19], v[166:169], v[210:213], v[16:19]
	v_mfma_f32_16x16x32_bf16 v[4:7], v[158:161], v[218:221], v[4:7]
	v_mfma_f32_16x16x32_bf16 v[0:3], v[166:169], v[218:221], v[0:3]
	v_mfma_f32_16x16x32_bf16 v[52:55], v[162:165], v[178:181], v[52:55]
	v_mfma_f32_16x16x32_bf16 v[48:51], v[170:173], v[178:181], v[48:51]
	v_mfma_f32_16x16x32_bf16 v[36:39], v[162:165], v[186:189], v[36:39]
	v_mfma_f32_16x16x32_bf16 v[32:35], v[170:173], v[186:189], v[32:35]
	v_mfma_f32_16x16x32_bf16 v[20:23], v[162:165], v[214:217], v[20:23]
	v_mfma_f32_16x16x32_bf16 v[16:19], v[170:173], v[214:217], v[16:19]
	v_mfma_f32_16x16x32_bf16 v[4:7], v[162:165], v[222:225], v[4:7]
	v_mfma_f32_16x16x32_bf16 v[0:3], v[170:173], v[222:225], v[0:3]
	s_setprio 0
	s_barrier
	s_add_i32 s28, 0, 0x18000
	s_add_i32 s29, 0, 0x1c000
	v_add_u32_e32 v154, s28, v147
	v_add_u32_e32 v170, s29, v147
	ds_read_b128 v[138:141], v154
	ds_read_b128 v[142:145], v154 offset:1024
	ds_read_b128 v[150:153], v154 offset:2048
	ds_read_b128 v[154:157], v154 offset:3072
	ds_read_b128 v[158:161], v170
	ds_read_b128 v[162:165], v170 offset:1024
	ds_read_b128 v[166:169], v170 offset:2048
	ds_read_b128 v[170:173], v170 offset:3072
	s_add_u32 s26, s62, 0x40000
	s_addc_u32 s27, s63, 0
	s_mov_b32 m0, s19
	v_lshl_add_u64 v[226:227], s[26:27], 0, v[132:133]
	ds_read_b128 v[174:177], v149 offset:32768
	ds_read_b128 v[178:181], v149 offset:33792
	ds_read_b128 v[182:185], v149 offset:34816
	ds_read_b128 v[186:189], v149 offset:35840
	ds_read_b128 v[210:213], v149 offset:36864
	ds_read_b128 v[214:217], v149 offset:37888
	ds_read_b128 v[218:221], v149 offset:38912
	ds_read_b128 v[222:225], v149 offset:39936
	global_load_lds_dwordx4 v[226:227], off
	v_lshl_add_u64 v[226:227], s[26:27], 0, v[130:131]
	s_mov_b32 m0, s20
	s_nop 0
	global_load_lds_dwordx4 v[226:227], off
	s_waitcnt vmcnt(8)
	s_waitcnt lgkmcnt(0)
	s_barrier
	s_setprio 1
	s_waitcnt lgkmcnt(0)
	v_mfma_f32_16x16x32_bf16 v[124:127], v[138:141], v[174:177], v[124:127]
	v_mfma_f32_16x16x32_bf16 v[120:123], v[150:153], v[174:177], v[120:123]
	v_mfma_f32_16x16x32_bf16 v[108:111], v[138:141], v[182:185], v[108:111]
	v_mfma_f32_16x16x32_bf16 v[104:107], v[150:153], v[182:185], v[104:107]
	v_mfma_f32_16x16x32_bf16 v[92:95], v[138:141], v[210:213], v[92:95]
	v_mfma_f32_16x16x32_bf16 v[88:91], v[150:153], v[210:213], v[88:91]
	v_mfma_f32_16x16x32_bf16 v[76:79], v[138:141], v[218:221], v[76:79]
	v_mfma_f32_16x16x32_bf16 v[72:75], v[150:153], v[218:221], v[72:75]
	v_mfma_f32_16x16x32_bf16 v[124:127], v[142:145], v[178:181], v[124:127]
	v_mfma_f32_16x16x32_bf16 v[120:123], v[154:157], v[178:181], v[120:123]
	v_mfma_f32_16x16x32_bf16 v[108:111], v[142:145], v[186:189], v[108:111]
	v_mfma_f32_16x16x32_bf16 v[104:107], v[154:157], v[186:189], v[104:107]
	v_mfma_f32_16x16x32_bf16 v[92:95], v[142:145], v[214:217], v[92:95]
	v_mfma_f32_16x16x32_bf16 v[88:91], v[154:157], v[214:217], v[88:91]
	v_mfma_f32_16x16x32_bf16 v[76:79], v[142:145], v[222:225], v[76:79]
	v_mfma_f32_16x16x32_bf16 v[72:75], v[154:157], v[222:225], v[72:75]
	v_mfma_f32_16x16x32_bf16 v[116:119], v[158:161], v[174:177], v[116:119]
	v_mfma_f32_16x16x32_bf16 v[112:115], v[166:169], v[174:177], v[112:115]
	v_mfma_f32_16x16x32_bf16 v[100:103], v[158:161], v[182:185], v[100:103]
	v_mfma_f32_16x16x32_bf16 v[96:99], v[166:169], v[182:185], v[96:99]
	v_mfma_f32_16x16x32_bf16 v[84:87], v[158:161], v[210:213], v[84:87]
	v_mfma_f32_16x16x32_bf16 v[80:83], v[166:169], v[210:213], v[80:83]
	v_mfma_f32_16x16x32_bf16 v[68:71], v[158:161], v[218:221], v[68:71]
	v_mfma_f32_16x16x32_bf16 v[64:67], v[166:169], v[218:221], v[64:67]
	v_mfma_f32_16x16x32_bf16 v[116:119], v[162:165], v[178:181], v[116:119]
	v_mfma_f32_16x16x32_bf16 v[112:115], v[170:173], v[178:181], v[112:115]
	v_mfma_f32_16x16x32_bf16 v[100:103], v[162:165], v[186:189], v[100:103]
	v_mfma_f32_16x16x32_bf16 v[96:99], v[170:173], v[186:189], v[96:99]
	v_mfma_f32_16x16x32_bf16 v[84:87], v[162:165], v[214:217], v[84:87]
	v_mfma_f32_16x16x32_bf16 v[80:83], v[170:173], v[214:217], v[80:83]
	v_mfma_f32_16x16x32_bf16 v[68:71], v[162:165], v[222:225], v[68:71]
	v_mfma_f32_16x16x32_bf16 v[64:67], v[170:173], v[222:225], v[64:67]
	s_setprio 0
	s_barrier
; #define PG8_STAGE(bufoff, gbase, voff) do { _Pragma("unroll") for (int _i = 0; _i < 2; ++_i) _Pragma("unroll") for (int _r = 0; _r < PG8_NREP; ++_r) \
;         __builtin_amdgcn_global_load_lds((const unsigned*)((const char*)(gbase) + (voff)[_i]), (PG8_LAS unsigned*)(lds + (bufoff) + ldsw + _i * 8192), 16, 0, 0); } while (0)
; #define PG8_LDA(dst, b, h) do { _Pragma("unroll") for (int m = 0; m < 4; ++m) _Pragma("unroll") for (int k = 0; k < 2; ++k) { dst[m][k] = *(const PG8_LAS bf16x8*)(lds + PG8_SA(b, h) + aoff + m * 2048 + k * 1024); PG8_DUP((unsigned)(uintptr_t)(lds + PG8_SA(b, h) + aoff + m * 2048 + k * 1024)); } } while (0)
; #define PG8_MMA(ai, bj, At, Bt) do { __builtin_amdgcn_s_setprio(1); _Pragma("unroll") for (int m = 0; m < 4; ++m) _Pragma("unroll") for (int n = 0; n < 2; ++n) _Pragma("unroll") for (int k = 0; k < 2; ++k) \
;         acc[ai][bj][m][n] = __builtin_amdgcn_mfma_f32_16x16x32_bf16(Bt[n][k], At[m][k], acc[ai][bj][m][n], 0, 0, 0); __builtin_amdgcn_s_setprio(0); } while (0)
; #define PG8_WAIT_V(n) do { if ((n) == 0) asm volatile("s_waitcnt vmcnt(0)" ::: "memory"); else if ((n) == 2) asm volatile("s_waitcnt vmcnt(4)" ::: "memory"); else if ((n) == 4) asm volatile("s_waitcnt vmcnt(8)" ::: "memory"); \
;     else if ((n) == 6) asm volatile("s_waitcnt vmcnt(12)" ::: "memory"); else asm volatile("s_waitcnt vmcnt(16)" ::: "memory"); } while (0)
; #define PG8_WAIT_V(n) asm volatile("s_waitcnt vmcnt(" #n ")" ::: "memory")
; #define PG8_WAIT_L(n) asm volatile("s_waitcnt lgkmcnt(" #n ")" ::: "memory")
; #define PG8_BAR __builtin_amdgcn_s_barrier()
; #define PG8_SCHED __builtin_amdgcn_sched_barrier(0)
; template <class Epi, class Sched, bool ALIGN_EPI = false, bool SP2 = false>
; __device__ __forceinline__ void gemm_phase(PG8_LAS unsigned char* lds, const Gemm g, const Sched& S, const Epi& E) {
;     ...
;             PG8_LDA(At, 1, 1); PG8_STAGE(PG8_SB(1, 0), b3, voffB); PG8_STAGE(PG8_SB(1, 1), b3 + hstepB, voffB); PG8_STAGE(PG8_SA(1, 0), a3, voffA);
;             PG8_WAIT_V(8); PG8_WAIT_L(0); PG8_BAR; PG8_MMA(1, 0, At, B0); PG8_MMA(1, 1, At, B1); PG8_BAR; PG8_SCHED;
;     ...
;         if constexpr (ALIGN_EPI) { if (wr == 0) PG8_BAR; }
	s_add_i32 s26, s28, s16
	v_lshl_add_u64 v[190:191], v[190:191], 0, s[68:69]
	s_mov_b32 m0, s26
	ds_read_b128 v[174:177], v149 offset:49152
	ds_read_b128 v[178:181], v149 offset:50176
	ds_read_b128 v[182:185], v149 offset:51200
	ds_read_b128 v[186:189], v149 offset:52224
	ds_read_b128 v[210:213], v149 offset:53248
	ds_read_b128 v[214:217], v149 offset:54272
	ds_read_b128 v[218:221], v149 offset:55296
	ds_read_b128 v[222:225], v149 offset:56320
	global_load_lds_dwordx4 v[190:191], off
	s_add_i32 m0, s26, 0x2000
	s_add_u32 s26, s58, 0x40080
	v_lshl_add_u64 v[190:191], v[194:195], 0, s[68:69]
	s_addc_u32 s27, s59, 0
	s_add_i32 s28, s29, s16
	global_load_lds_dwordx4 v[190:191], off
	v_lshl_add_u64 v[190:191], s[26:27], 0, v[192:193]
	s_mov_b32 m0, s28
	s_nop 0
	global_load_lds_dwordx4 v[190:191], off
	v_lshl_add_u64 v[190:191], s[26:27], 0, v[128:129]
	s_add_i32 m0, s28, 0x2000
	s_nop 0
	global_load_lds_dwordx4 v[190:191], off
	v_lshl_add_u64 v[190:191], v[196:197], 0, s[68:69]
	s_mov_b32 m0, s21
	s_nop 0
	global_load_lds_dwordx4 v[190:191], off
	v_lshl_add_u64 v[190:191], v[200:201], 0, s[68:69]
	s_mov_b32 m0, s22
	s_nop 0
	global_load_lds_dwordx4 v[190:191], off
	s_waitcnt vmcnt(8)
	s_waitcnt lgkmcnt(0)
	s_barrier
	s_setprio 1
	s_waitcnt lgkmcnt(0)
	v_mfma_f32_16x16x32_bf16 v[60:63], v[138:141], v[174:177], v[60:63]
	v_mfma_f32_16x16x32_bf16 v[56:59], v[150:153], v[174:177], v[56:59]
	v_mfma_f32_16x16x32_bf16 v[44:47], v[138:141], v[182:185], v[44:47]
	v_mfma_f32_16x16x32_bf16 v[40:43], v[150:153], v[182:185], v[40:43]
	v_mfma_f32_16x16x32_bf16 v[28:31], v[138:141], v[210:213], v[28:31]
	v_mfma_f32_16x16x32_bf16 v[24:27], v[150:153], v[210:213], v[24:27]
	v_mfma_f32_16x16x32_bf16 v[12:15], v[138:141], v[218:221], v[12:15]
	v_mfma_f32_16x16x32_bf16 v[8:11], v[150:153], v[218:221], v[8:11]
	v_mfma_f32_16x16x32_bf16 v[60:63], v[142:145], v[178:181], v[60:63]
	v_mfma_f32_16x16x32_bf16 v[56:59], v[154:157], v[178:181], v[56:59]
	v_mfma_f32_16x16x32_bf16 v[44:47], v[142:145], v[186:189], v[44:47]
	v_mfma_f32_16x16x32_bf16 v[40:43], v[154:157], v[186:189], v[40:43]
	v_mfma_f32_16x16x32_bf16 v[28:31], v[142:145], v[214:217], v[28:31]
	v_mfma_f32_16x16x32_bf16 v[24:27], v[154:157], v[214:217], v[24:27]
	v_mfma_f32_16x16x32_bf16 v[12:15], v[142:145], v[222:225], v[12:15]
	v_mfma_f32_16x16x32_bf16 v[8:11], v[154:157], v[222:225], v[8:11]
	v_mfma_f32_16x16x32_bf16 v[52:55], v[158:161], v[174:177], v[52:55]
	v_mfma_f32_16x16x32_bf16 v[48:51], v[166:169], v[174:177], v[48:51]
	v_mfma_f32_16x16x32_bf16 v[36:39], v[158:161], v[182:185], v[36:39]
	v_mfma_f32_16x16x32_bf16 v[32:35], v[166:169], v[182:185], v[32:35]
	v_mfma_f32_16x16x32_bf16 v[20:23], v[158:161], v[210:213], v[20:23]
	v_mfma_f32_16x16x32_bf16 v[16:19], v[166:169], v[210:213], v[16:19]
	v_mfma_f32_16x16x32_bf16 v[4:7], v[158:161], v[218:221], v[4:7]
	v_mfma_f32_16x16x32_bf16 v[0:3], v[166:169], v[218:221], v[0:3]
	v_mfma_f32_16x16x32_bf16 v[52:55], v[162:165], v[178:181], v[52:55]
	v_mfma_f32_16x16x32_bf16 v[48:51], v[170:173], v[178:181], v[48:51]
	v_mfma_f32_16x16x32_bf16 v[36:39], v[162:165], v[186:189], v[36:39]
	v_mfma_f32_16x16x32_bf16 v[32:35], v[170:173], v[186:189], v[32:35]
	v_mfma_f32_16x16x32_bf16 v[20:23], v[162:165], v[214:217], v[20:23]
	v_mfma_f32_16x16x32_bf16 v[16:19], v[170:173], v[214:217], v[16:19]
	v_mfma_f32_16x16x32_bf16 v[4:7], v[162:165], v[222:225], v[4:7]
	v_mfma_f32_16x16x32_bf16 v[0:3], v[170:173], v[222:225], v[0:3]
	s_setprio 0
	s_barrier
	s_add_i32 s25, s25, 2
	s_add_u32 s54, s54, 0x100
	s_addc_u32 s55, s55, 0
	s_add_u32 s94, s94, 0x100
	s_addc_u32 s24, s24, 0
	s_cmp_gt_u32 s25, 13
	s_cbranch_scc0 .LBB0_612
	s_and_b64 vcc, exec, s[40:41]
	s_cbranch_vccz .LBB0_615
	s_barrier

; #define PG8_STAGE(bufoff, gbase, voff) do { _Pragma("unroll") for (int _i = 0; _i < 2; ++_i) _Pragma("unroll") for (int _r = 0; _r < PG8_NREP; ++_r) \
;         __builtin_amdgcn_global_load_lds((const unsigned*)((const char*)(gbase) + (voff)[_i]), (PG8_LAS unsigned*)(lds + (bufoff) + ldsw + _i * 8192), 16, 0, 0); } while (0)
; #define PG8_LDA(dst, b, h) do { _Pragma("unroll") for (int m = 0; m < 4; ++m) _Pragma("unroll") for (int k = 0; k < 2; ++k) { dst[m][k] = *(const PG8_LAS bf16x8*)(lds + PG8_SA(b, h) + aoff + m * 2048 + k * 1024); PG8_DUP((unsigned)(uintptr_t)(lds + PG8_SA(b, h) + aoff + m * 2048 + k * 1024)); } } while (0)
; #define PG8_LDB(dst, b, h) do { _Pragma("unroll") for (int n = 0; n < 2; ++n) _Pragma("unroll") for (int k = 0; k < 2; ++k) { dst[n][k] = *(const PG8_LAS bf16x8*)(lds + PG8_SB(b, h) + boff + n * 2048 + k * 1024); PG8_DUP((unsigned)(uintptr_t)(lds + PG8_SB(b, h) + boff + n * 2048 + k * 1024)); } } while (0)
; #define PG8_MMA(ai, bj, At, Bt) do { __builtin_amdgcn_s_setprio(1); _Pragma("unroll") for (int m = 0; m < 4; ++m) _Pragma("unroll") for (int n = 0; n < 2; ++n) _Pragma("unroll") for (int k = 0; k < 2; ++k) \
;         acc[ai][bj][m][n] = __builtin_amdgcn_mfma_f32_16x16x32_bf16(Bt[n][k], At[m][k], acc[ai][bj][m][n], 0, 0, 0); __builtin_amdgcn_s_setprio(0); } while (0)
; template <class Epi, class Sched, bool ALIGN_EPI = false, bool SP2 = false>
; __device__ __forceinline__ void gemm_phase(PG8_LAS unsigned char* lds, const Gemm g, const Sched& S, const Epi& E) {
;     ...
;             const bool last = (t == nt - 2);
;             const char* a1 = cA + (size_t)(t + 1) * kstep;
;             const char* a2 = last ? nA : cA + (size_t)(t + 2) * kstep; const char* b2 = last ? nB : cB + (size_t)(t + 2) * kstep;
;             const char* a3 = a2 + kstep; const char* b3 = b2 + kstep;
;             if (last && has_next) S.a_ready(nxt);
;             if constexpr (SP2) {
;     ...
;             if (Epi::PERM && sizeof(Epi) && TEST_DRAIN) PG8_WAIT_V(0);
;     ...
;             PG8_LDB(B0, 0, 0); PG8_LDB(B1, 0, 1); PG8_SCHED; PG8_LDA(At, 0, 0); PG8_STAGE(PG8_SA(1, 1), a1 + hstepA, voffA);
;             PG8_WAIT_V(8); PG8_WAIT_L(0); PG8_BAR; PG8_MMA(0, 0, At, B0); PG8_MMA(0, 1, At, B1); PG8_BAR; PG8_SCHED;
;             PG8_LDA(At, 0, 1); PG8_STAGE(PG8_SB(0, 0), b2, voffB); PG8_STAGE(PG8_SB(0, 1), b2 + hstepB, voffB); PG8_STAGE(PG8_SA(0, 0), a2, voffA);
.LBB0_684:
	s_add_u32 s26, s14, 0xfff80080
	s_addc_u32 s27, s15, -1
	s_add_i32 s28, 0, 0x10000
	s_cmp_eq_u32 s25, 28
	s_cselect_b32 s95, s23, s27
	s_cselect_b32 s94, s63, s26
	s_cselect_b32 s93, s55, s24
	s_cselect_b32 s92, vcc_lo, vcc_hi
	s_add_i32 s29, 0, 0x14000
	v_add_u32_e32 v52, s28, v165
	v_add_u32_e32 v162, s29, v165
	ds_read_b128 v[24:27], v52
	ds_read_b128 v[28:31], v52 offset:1024
	ds_read_b128 v[48:51], v52 offset:2048
	ds_read_b128 v[52:55], v52 offset:3072
	ds_read_b128 v[154:157], v162
	ds_read_b128 v[158:161], v162 offset:1024
	ds_read_b128 v[168:171], v162 offset:2048
	ds_read_b128 v[172:175], v162 offset:3072
	v_lshl_add_u64 v[162:163], s[14:15], 0, v[150:151]
	s_add_i32 m0, s91, 0xc000
	ds_read_b128 v[176:179], v167
	ds_read_b128 v[180:183], v167 offset:1024
	ds_read_b128 v[184:187], v167 offset:2048
	ds_read_b128 v[188:191], v167 offset:3072
	ds_read_b128 v[210:213], v167 offset:4096
	ds_read_b128 v[214:217], v167 offset:5120
	ds_read_b128 v[218:221], v167 offset:6144
	ds_read_b128 v[222:225], v167 offset:7168
	global_load_lds_dwordx4 v[162:163], off
	v_lshl_add_u64 v[162:163], s[14:15], 0, v[152:153]
	s_add_i32 m0, s91, 0xe000
	s_nop 0
	global_load_lds_dwordx4 v[162:163], off
	s_waitcnt vmcnt(8)
	s_waitcnt lgkmcnt(0)
	s_barrier
	s_setprio 1
	s_waitcnt lgkmcnt(0)
	v_mfma_f32_16x16x32_bf16 v[140:143], v[24:27], v[176:179], v[140:143]
	v_mfma_f32_16x16x32_bf16 v[136:139], v[48:51], v[176:179], v[136:139]
	v_mfma_f32_16x16x32_bf16 v[124:127], v[24:27], v[184:187], v[124:127]
	v_mfma_f32_16x16x32_bf16 v[120:123], v[48:51], v[184:187], v[120:123]
	v_mfma_f32_16x16x32_bf16 v[108:111], v[24:27], v[210:213], v[108:111]
	v_mfma_f32_16x16x32_bf16 v[104:107], v[48:51], v[210:213], v[104:107]
	v_mfma_f32_16x16x32_bf16 v[92:95], v[24:27], v[218:221], v[92:95]
	v_mfma_f32_16x16x32_bf16 v[88:91], v[48:51], v[218:221], v[88:91]
	v_mfma_f32_16x16x32_bf16 v[140:143], v[28:31], v[180:183], v[140:143]
	v_mfma_f32_16x16x32_bf16 v[136:139], v[52:55], v[180:183], v[136:139]
	v_mfma_f32_16x16x32_bf16 v[124:127], v[28:31], v[188:191], v[124:127]
	v_mfma_f32_16x16x32_bf16 v[120:123], v[52:55], v[188:191], v[120:123]
	v_mfma_f32_16x16x32_bf16 v[108:111], v[28:31], v[214:217], v[108:111]
	v_mfma_f32_16x16x32_bf16 v[104:107], v[52:55], v[214:217], v[104:107]
	v_mfma_f32_16x16x32_bf16 v[92:95], v[28:31], v[222:225], v[92:95]
	v_mfma_f32_16x16x32_bf16 v[88:91], v[52:55], v[222:225], v[88:91]
	v_mfma_f32_16x16x32_bf16 v[132:135], v[154:157], v[176:179], v[132:135]
	v_mfma_f32_16x16x32_bf16 v[128:131], v[168:171], v[176:179], v[128:131]
	v_mfma_f32_16x16x32_bf16 v[116:119], v[154:157], v[184:187], v[116:119]
	v_mfma_f32_16x16x32_bf16 v[112:115], v[168:171], v[184:187], v[112:115]
	v_mfma_f32_16x16x32_bf16 v[100:103], v[154:157], v[210:213], v[100:103]
	v_mfma_f32_16x16x32_bf16 v[96:99], v[168:171], v[210:213], v[96:99]
	v_mfma_f32_16x16x32_bf16 v[84:87], v[154:157], v[218:221], v[84:87]
	v_mfma_f32_16x16x32_bf16 v[80:83], v[168:171], v[218:221], v[80:83]
	v_mfma_f32_16x16x32_bf16 v[132:135], v[158:161], v[180:183], v[132:135]
	v_mfma_f32_16x16x32_bf16 v[128:131], v[172:175], v[180:183], v[128:131]
	v_mfma_f32_16x16x32_bf16 v[116:119], v[158:161], v[188:191], v[116:119]
	v_mfma_f32_16x16x32_bf16 v[112:115], v[172:175], v[188:191], v[112:115]
	v_mfma_f32_16x16x32_bf16 v[100:103], v[158:161], v[214:217], v[100:103]
	v_mfma_f32_16x16x32_bf16 v[96:99], v[172:175], v[214:217], v[96:99]
	v_mfma_f32_16x16x32_bf16 v[84:87], v[158:161], v[222:225], v[84:87]
	v_mfma_f32_16x16x32_bf16 v[80:83], v[172:175], v[222:225], v[80:83]
	s_setprio 0
	s_barrier
	s_add_i32 s26, s28, s86
	v_lshl_add_u64 v[162:163], s[92:93], 0, v[192:193]
	s_mov_b32 m0, s26
	ds_read_b128 v[176:179], v167 offset:16384
	ds_read_b128 v[180:183], v167 offset:17408
	ds_read_b128 v[184:187], v167 offset:18432
	ds_read_b128 v[188:191], v167 offset:19456
	ds_read_b128 v[210:213], v167 offset:20480
	ds_read_b128 v[214:217], v167 offset:21504
	ds_read_b128 v[218:221], v167 offset:22528
	ds_read_b128 v[222:225], v167 offset:23552
	global_load_lds_dwordx4 v[162:163], off
	s_add_i32 m0, s26, 0x2000
	s_add_u32 s26, s92, 0x80000
	v_lshl_add_u64 v[194:195], s[92:93], 0, v[144:145]
	s_addc_u32 s27, s93, 0
	s_add_i32 s28, s29, s86
	global_load_lds_dwordx4 v[194:195], off
	v_lshl_add_u64 v[196:197], s[26:27], 0, v[192:193]
	s_mov_b32 m0, s28
	v_lshl_add_u64 v[200:201], s[94:95], 0, v[146:147]
	global_load_lds_dwordx4 v[196:197], off
	v_lshl_add_u64 v[196:197], s[26:27], 0, v[144:145]
	s_add_i32 m0, s28, 0x2000
	s_nop 0
	global_load_lds_dwordx4 v[196:197], off
	v_lshl_add_u64 v[196:197], s[94:95], 0, v[148:149]
	s_mov_b32 m0, s91
	s_nop 0
	global_load_lds_dwordx4 v[196:197], off
	s_mov_b32 m0, s97
	s_nop 0
	global_load_lds_dwordx4 v[200:201], off
	s_waitcnt vmcnt(8)
	s_waitcnt lgkmcnt(0)
	s_barrier
; #define PG8_STAGE(bufoff, gbase, voff) do { _Pragma("unroll") for (int _i = 0; _i < 2; ++_i) _Pragma("unroll") for (int _r = 0; _r < PG8_NREP; ++_r) \
;         __builtin_amdgcn_global_load_lds((const unsigned*)((const char*)(gbase) + (voff)[_i]), (PG8_LAS unsigned*)(lds + (bufoff) + ldsw + _i * 8192), 16, 0, 0); } while (0)
; #define PG8_LDA(dst, b, h) do { _Pragma("unroll") for (int m = 0; m < 4; ++m) _Pragma("unroll") for (int k = 0; k < 2; ++k) { dst[m][k] = *(const PG8_LAS bf16x8*)(lds + PG8_SA(b, h) + aoff + m * 2048 + k * 1024); PG8_DUP((unsigned)(uintptr_t)(lds + PG8_SA(b, h) + aoff + m * 2048 + k * 1024)); } } while (0)
; #define PG8_LDB(dst, b, h) do { _Pragma("unroll") for (int n = 0; n < 2; ++n) _Pragma("unroll") for (int k = 0; k < 2; ++k) { dst[n][k] = *(const PG8_LAS bf16x8*)(lds + PG8_SB(b, h) + boff + n * 2048 + k * 1024); PG8_DUP((unsigned)(uintptr_t)(lds + PG8_SB(b, h) + boff + n * 2048 + k * 1024)); } } while (0)
; #define PG8_MMA(ai, bj, At, Bt) do { __builtin_amdgcn_s_setprio(1); _Pragma("unroll") for (int m = 0; m < 4; ++m) _Pragma("unroll") for (int n = 0; n < 2; ++n) _Pragma("unroll") for (int k = 0; k < 2; ++k) \
;         acc[ai][bj][m][n] = __builtin_amdgcn_mfma_f32_16x16x32_bf16(Bt[n][k], At[m][k], acc[ai][bj][m][n], 0, 0, 0); __builtin_amdgcn_s_setprio(0); } while (0)
; #define PG8_WAIT_V(n) do { if ((n) == 0) asm volatile("s_waitcnt vmcnt(0)" ::: "memory"); else if ((n) == 2) asm volatile("s_waitcnt vmcnt(4)" ::: "memory"); else if ((n) == 4) asm volatile("s_waitcnt vmcnt(8)" ::: "memory"); \
;     else if ((n) == 6) asm volatile("s_waitcnt vmcnt(12)" ::: "memory"); else asm volatile("s_waitcnt vmcnt(16)" ::: "memory"); } while (0)
; #define PG8_WAIT_V(n) asm volatile("s_waitcnt vmcnt(" #n ")" ::: "memory")
; #define PG8_BAR __builtin_amdgcn_s_barrier()
; template <class Epi, class Sched, bool ALIGN_EPI = false, bool SP2 = false>
; __device__ __forceinline__ void gemm_phase(PG8_LAS unsigned char* lds, const Gemm g, const Sched& S, const Epi& E) {
;     ...
;             PG8_WAIT_V(8); PG8_WAIT_L(0); PG8_BAR; PG8_MMA(1, 0, At, B0); PG8_MMA(1, 1, At, B1); PG8_BAR; PG8_SCHED;
;             PG8_LDB(B0, 1, 0); PG8_LDB(B1, 1, 1); PG8_SCHED; PG8_LDA(At, 1, 0); PG8_STAGE(PG8_SA(0, 1), a2 + hstepA, voffA);
;             PG8_WAIT_V(8); PG8_WAIT_L(0); PG8_BAR; PG8_MMA(0, 0, At, B0); PG8_MMA(0, 1, At, B1); PG8_BAR; PG8_SCHED;
	s_setprio 1
	s_waitcnt lgkmcnt(0)
	v_mfma_f32_16x16x32_bf16 v[76:79], v[24:27], v[176:179], v[76:79]
	v_mfma_f32_16x16x32_bf16 v[72:75], v[48:51], v[176:179], v[72:75]
	v_mfma_f32_16x16x32_bf16 v[60:63], v[24:27], v[184:187], v[60:63]
	v_mfma_f32_16x16x32_bf16 v[56:59], v[48:51], v[184:187], v[56:59]
	v_mfma_f32_16x16x32_bf16 v[36:39], v[24:27], v[210:213], v[36:39]
	v_mfma_f32_16x16x32_bf16 v[32:35], v[48:51], v[210:213], v[32:35]
	v_mfma_f32_16x16x32_bf16 v[12:15], v[24:27], v[218:221], v[12:15]
	v_mfma_f32_16x16x32_bf16 v[8:11], v[48:51], v[218:221], v[8:11]
	v_mfma_f32_16x16x32_bf16 v[76:79], v[28:31], v[180:183], v[76:79]
	v_mfma_f32_16x16x32_bf16 v[72:75], v[52:55], v[180:183], v[72:75]
	v_mfma_f32_16x16x32_bf16 v[60:63], v[28:31], v[188:191], v[60:63]
	v_mfma_f32_16x16x32_bf16 v[56:59], v[52:55], v[188:191], v[56:59]
	v_mfma_f32_16x16x32_bf16 v[36:39], v[28:31], v[214:217], v[36:39]
	v_mfma_f32_16x16x32_bf16 v[32:35], v[52:55], v[214:217], v[32:35]
	v_mfma_f32_16x16x32_bf16 v[12:15], v[28:31], v[222:225], v[12:15]
	v_mfma_f32_16x16x32_bf16 v[8:11], v[52:55], v[222:225], v[8:11]
	v_mfma_f32_16x16x32_bf16 v[44:47], v[154:157], v[184:187], v[44:47]
	v_mfma_f32_16x16x32_bf16 v[40:43], v[168:171], v[184:187], v[40:43]
	v_mfma_f32_16x16x32_bf16 v[20:23], v[154:157], v[210:213], v[20:23]
	v_mfma_f32_16x16x32_bf16 v[16:19], v[168:171], v[210:213], v[16:19]
	v_mfma_f32_16x16x32_bf16 v[4:7], v[154:157], v[218:221], v[4:7]
	v_mfma_f32_16x16x32_bf16 v[0:3], v[168:171], v[218:221], v[0:3]
	v_mfma_f32_16x16x32_bf16 v[24:27], v[154:157], v[176:179], v[68:71]
	v_mfma_f32_16x16x32_bf16 v[28:31], v[168:171], v[176:179], v[64:67]
	v_mfma_f32_16x16x32_bf16 v[44:47], v[158:161], v[188:191], v[44:47]
	v_mfma_f32_16x16x32_bf16 v[40:43], v[172:175], v[188:191], v[40:43]
	v_mfma_f32_16x16x32_bf16 v[20:23], v[158:161], v[214:217], v[20:23]
	v_mfma_f32_16x16x32_bf16 v[16:19], v[172:175], v[214:217], v[16:19]
	v_mfma_f32_16x16x32_bf16 v[4:7], v[158:161], v[222:225], v[4:7]
	v_mfma_f32_16x16x32_bf16 v[0:3], v[172:175], v[222:225], v[0:3]
	v_mfma_f32_16x16x32_bf16 v[24:27], v[158:161], v[180:183], v[24:27]
	v_mfma_f32_16x16x32_bf16 v[28:31], v[172:175], v[180:183], v[28:31]
	s_setprio 0
	s_barrier
	s_add_i32 s28, 0, 0x18000
	s_add_i32 s29, 0, 0x1c000
	v_add_u32_e32 v68, s28, v165
	v_add_u32_e32 v172, s29, v165
	ds_read_b128 v[48:51], v68
	ds_read_b128 v[52:55], v68 offset:1024
	ds_read_b128 v[64:67], v68 offset:2048
	ds_read_b128 v[68:71], v68 offset:3072
	ds_read_b128 v[154:157], v172
	ds_read_b128 v[158:161], v172 offset:1024
	ds_read_b128 v[168:171], v172 offset:2048
	ds_read_b128 v[172:175], v172 offset:3072
	s_add_u32 s26, s94, 0x80000
	s_addc_u32 s27, s95, 0
	s_mov_b32 m0, s16
	v_lshl_add_u64 v[226:227], s[26:27], 0, v[148:149]
	ds_read_b128 v[176:179], v167 offset:32768
	ds_read_b128 v[180:183], v167 offset:33792
	ds_read_b128 v[184:187], v167 offset:34816
	ds_read_b128 v[188:191], v167 offset:35840
	ds_read_b128 v[210:213], v167 offset:36864
	ds_read_b128 v[214:217], v167 offset:37888
	ds_read_b128 v[218:221], v167 offset:38912
	ds_read_b128 v[222:225], v167 offset:39936
	global_load_lds_dwordx4 v[226:227], off
	v_lshl_add_u64 v[226:227], s[26:27], 0, v[146:147]
	s_mov_b32 m0, s17
	s_nop 0
	global_load_lds_dwordx4 v[226:227], off
	s_waitcnt vmcnt(8)
	s_waitcnt lgkmcnt(0)
	s_barrier
	s_setprio 1
	s_waitcnt lgkmcnt(0)
	v_mfma_f32_16x16x32_bf16 v[140:143], v[48:51], v[176:179], v[140:143]
	v_mfma_f32_16x16x32_bf16 v[136:139], v[64:67], v[176:179], v[136:139]
	v_mfma_f32_16x16x32_bf16 v[124:127], v[48:51], v[184:187], v[124:127]
	v_mfma_f32_16x16x32_bf16 v[120:123], v[64:67], v[184:187], v[120:123]
	v_mfma_f32_16x16x32_bf16 v[108:111], v[48:51], v[210:213], v[108:111]
	v_mfma_f32_16x16x32_bf16 v[104:107], v[64:67], v[210:213], v[104:107]
	v_mfma_f32_16x16x32_bf16 v[92:95], v[48:51], v[218:221], v[92:95]
	v_mfma_f32_16x16x32_bf16 v[88:91], v[64:67], v[218:221], v[88:91]
	v_mfma_f32_16x16x32_bf16 v[140:143], v[52:55], v[180:183], v[140:143]
	v_mfma_f32_16x16x32_bf16 v[136:139], v[68:71], v[180:183], v[136:139]
	v_mfma_f32_16x16x32_bf16 v[124:127], v[52:55], v[188:191], v[124:127]
	v_mfma_f32_16x16x32_bf16 v[120:123], v[68:71], v[188:191], v[120:123]
	v_mfma_f32_16x16x32_bf16 v[108:111], v[52:55], v[214:217], v[108:111]
	v_mfma_f32_16x16x32_bf16 v[104:107], v[68:71], v[214:217], v[104:107]
	v_mfma_f32_16x16x32_bf16 v[92:95], v[52:55], v[222:225], v[92:95]
	v_mfma_f32_16x16x32_bf16 v[88:91], v[68:71], v[222:225], v[88:91]
	v_mfma_f32_16x16x32_bf16 v[132:135], v[154:157], v[176:179], v[132:135]
	v_mfma_f32_16x16x32_bf16 v[128:131], v[168:171], v[176:179], v[128:131]
	v_mfma_f32_16x16x32_bf16 v[116:119], v[154:157], v[184:187], v[116:119]
	v_mfma_f32_16x16x32_bf16 v[112:115], v[168:171], v[184:187], v[112:115]
	v_mfma_f32_16x16x32_bf16 v[100:103], v[154:157], v[210:213], v[100:103]
	v_mfma_f32_16x16x32_bf16 v[96:99], v[168:171], v[210:213], v[96:99]
	v_mfma_f32_16x16x32_bf16 v[84:87], v[154:157], v[218:221], v[84:87]
	v_mfma_f32_16x16x32_bf16 v[80:83], v[168:171], v[218:221], v[80:83]
	v_mfma_f32_16x16x32_bf16 v[132:135], v[158:161], v[180:183], v[132:135]
	v_mfma_f32_16x16x32_bf16 v[128:131], v[172:175], v[180:183], v[128:131]
	v_mfma_f32_16x16x32_bf16 v[116:119], v[158:161], v[188:191], v[116:119]
	v_mfma_f32_16x16x32_bf16 v[112:115], v[172:175], v[188:191], v[112:115]
	v_mfma_f32_16x16x32_bf16 v[100:103], v[158:161], v[214:217], v[100:103]
	v_mfma_f32_16x16x32_bf16 v[96:99], v[172:175], v[214:217], v[96:99]
	v_mfma_f32_16x16x32_bf16 v[84:87], v[158:161], v[222:225], v[84:87]
	v_mfma_f32_16x16x32_bf16 v[80:83], v[172:175], v[222:225], v[80:83]
	s_setprio 0
	s_barrier
; #define PG8_STAGE(bufoff, gbase, voff) do { _Pragma("unroll") for (int _i = 0; _i < 2; ++_i) _Pragma("unroll") for (int _r = 0; _r < PG8_NREP; ++_r) \
;         __builtin_amdgcn_global_load_lds((const unsigned*)((const char*)(gbase) + (voff)[_i]), (PG8_LAS unsigned*)(lds + (bufoff) + ldsw + _i * 8192), 16, 0, 0); } while (0)
; #define PG8_LDA(dst, b, h) do { _Pragma("unroll") for (int m = 0; m < 4; ++m) _Pragma("unroll") for (int k = 0; k < 2; ++k) { dst[m][k] = *(const PG8_LAS bf16x8*)(lds + PG8_SA(b, h) + aoff + m * 2048 + k * 1024); PG8_DUP((unsigned)(uintptr_t)(lds + PG8_SA(b, h) + aoff + m * 2048 + k * 1024)); } } while (0)
; #define PG8_MMA(ai, bj, At, Bt) do { __builtin_amdgcn_s_setprio(1); _Pragma("unroll") for (int m = 0; m < 4; ++m) _Pragma("unroll") for (int n = 0; n < 2; ++n) _Pragma("unroll") for (int k = 0; k < 2; ++k) \
;         acc[ai][bj][m][n] = __builtin_amdgcn_mfma_f32_16x16x32_bf16(Bt[n][k], At[m][k], acc[ai][bj][m][n], 0, 0, 0); __builtin_amdgcn_s_setprio(0); } while (0)
; #define PG8_WAIT_V(n) do { if ((n) == 0) asm volatile("s_waitcnt vmcnt(0)" ::: "memory"); else if ((n) == 2) asm volatile("s_waitcnt vmcnt(4)" ::: "memory"); else if ((n) == 4) asm volatile("s_waitcnt vmcnt(8)" ::: "memory"); \
;     else if ((n) == 6) asm volatile("s_waitcnt vmcnt(12)" ::: "memory"); else asm volatile("s_waitcnt vmcnt(16)" ::: "memory"); } while (0)
; #define PG8_WAIT_V(n) asm volatile("s_waitcnt vmcnt(" #n ")" ::: "memory")
; #define PG8_WAIT_L(n) asm volatile("s_waitcnt lgkmcnt(" #n ")" ::: "memory")
; #define PG8_BAR __builtin_amdgcn_s_barrier()
; #define PG8_SCHED __builtin_amdgcn_sched_barrier(0)
; template <class Epi, class Sched, bool ALIGN_EPI = false, bool SP2 = false>
; __device__ __forceinline__ void gemm_phase(PG8_LAS unsigned char* lds, const Gemm g, const Sched& S, const Epi& E) {
;     ...
;             PG8_LDA(At, 1, 1); PG8_STAGE(PG8_SB(1, 0), b3, voffB); PG8_STAGE(PG8_SB(1, 1), b3 + hstepB, voffB); PG8_STAGE(PG8_SA(1, 0), a3, voffA);
;             PG8_WAIT_V(8); PG8_WAIT_L(0); PG8_BAR; PG8_MMA(1, 0, At, B0); PG8_MMA(1, 1, At, B1); PG8_BAR; PG8_SCHED;
;     ...
;         if constexpr (ALIGN_EPI) { if (wr == 0) PG8_BAR; }
	s_add_i32 s26, s28, s86
	v_lshl_add_u64 v[162:163], v[162:163], 0, s[68:69]
	s_mov_b32 m0, s26
	ds_read_b128 v[176:179], v167 offset:49152
	ds_read_b128 v[180:183], v167 offset:50176
	ds_read_b128 v[184:187], v167 offset:51200
	ds_read_b128 v[188:191], v167 offset:52224
	ds_read_b128 v[210:213], v167 offset:53248
	ds_read_b128 v[214:217], v167 offset:54272
	ds_read_b128 v[218:221], v167 offset:55296
	ds_read_b128 v[222:225], v167 offset:56320
	global_load_lds_dwordx4 v[162:163], off
	s_add_i32 m0, s26, 0x2000
	s_add_u32 s26, s92, 0x80080
	v_lshl_add_u64 v[162:163], v[194:195], 0, s[68:69]
	s_addc_u32 s27, s93, 0
	s_add_i32 s28, s29, s86
	global_load_lds_dwordx4 v[162:163], off
	v_lshl_add_u64 v[162:163], s[26:27], 0, v[192:193]
	s_mov_b32 m0, s28
	s_nop 0
	global_load_lds_dwordx4 v[162:163], off
	v_lshl_add_u64 v[162:163], s[26:27], 0, v[144:145]
	s_add_i32 m0, s28, 0x2000
	s_nop 0
	global_load_lds_dwordx4 v[162:163], off
	v_lshl_add_u64 v[162:163], v[196:197], 0, s[68:69]
	s_mov_b32 m0, s18
	s_nop 0
	global_load_lds_dwordx4 v[162:163], off
	v_lshl_add_u64 v[162:163], v[200:201], 0, s[68:69]
	s_mov_b32 m0, s19
	s_nop 0
	global_load_lds_dwordx4 v[162:163], off
	s_waitcnt vmcnt(8)
	s_waitcnt lgkmcnt(0)
	s_barrier
	s_setprio 1
	s_waitcnt lgkmcnt(0)
	v_mfma_f32_16x16x32_bf16 v[76:79], v[48:51], v[176:179], v[76:79]
	v_mfma_f32_16x16x32_bf16 v[72:75], v[64:67], v[176:179], v[72:75]
	v_mfma_f32_16x16x32_bf16 v[60:63], v[48:51], v[184:187], v[60:63]
	v_mfma_f32_16x16x32_bf16 v[56:59], v[64:67], v[184:187], v[56:59]
	v_mfma_f32_16x16x32_bf16 v[36:39], v[48:51], v[210:213], v[36:39]
	v_mfma_f32_16x16x32_bf16 v[32:35], v[64:67], v[210:213], v[32:35]
	v_mfma_f32_16x16x32_bf16 v[12:15], v[48:51], v[218:221], v[12:15]
	v_mfma_f32_16x16x32_bf16 v[8:11], v[64:67], v[218:221], v[8:11]
	v_mfma_f32_16x16x32_bf16 v[76:79], v[52:55], v[180:183], v[76:79]
	v_mfma_f32_16x16x32_bf16 v[72:75], v[68:71], v[180:183], v[72:75]
	v_mfma_f32_16x16x32_bf16 v[60:63], v[52:55], v[188:191], v[60:63]
	v_mfma_f32_16x16x32_bf16 v[56:59], v[68:71], v[188:191], v[56:59]
	v_mfma_f32_16x16x32_bf16 v[36:39], v[52:55], v[214:217], v[36:39]
	v_mfma_f32_16x16x32_bf16 v[32:35], v[68:71], v[214:217], v[32:35]
	v_mfma_f32_16x16x32_bf16 v[12:15], v[52:55], v[222:225], v[12:15]
	v_mfma_f32_16x16x32_bf16 v[8:11], v[68:71], v[222:225], v[8:11]
	v_mfma_f32_16x16x32_bf16 v[24:27], v[154:157], v[176:179], v[24:27]
	v_mfma_f32_16x16x32_bf16 v[68:71], v[158:161], v[180:183], v[24:27]
	v_mfma_f32_16x16x32_bf16 v[24:27], v[168:171], v[176:179], v[28:31]
	v_mfma_f32_16x16x32_bf16 v[64:67], v[172:175], v[180:183], v[24:27]
	v_mfma_f32_16x16x32_bf16 v[24:27], v[154:157], v[184:187], v[44:47]
	v_mfma_f32_16x16x32_bf16 v[44:47], v[158:161], v[188:191], v[24:27]
	v_mfma_f32_16x16x32_bf16 v[24:27], v[168:171], v[184:187], v[40:43]
	v_mfma_f32_16x16x32_bf16 v[20:23], v[154:157], v[210:213], v[20:23]
	v_mfma_f32_16x16x32_bf16 v[16:19], v[168:171], v[210:213], v[16:19]
	v_mfma_f32_16x16x32_bf16 v[4:7], v[154:157], v[218:221], v[4:7]
	v_mfma_f32_16x16x32_bf16 v[0:3], v[168:171], v[218:221], v[0:3]
	v_mfma_f32_16x16x32_bf16 v[40:43], v[172:175], v[188:191], v[24:27]
	v_mfma_f32_16x16x32_bf16 v[20:23], v[158:161], v[214:217], v[20:23]
	v_mfma_f32_16x16x32_bf16 v[16:19], v[172:175], v[214:217], v[16:19]
	v_mfma_f32_16x16x32_bf16 v[4:7], v[158:161], v[222:225], v[4:7]
	v_mfma_f32_16x16x32_bf16 v[0:3], v[172:175], v[222:225], v[0:3]
	s_setprio 0
	s_barrier
	s_add_i32 s25, s25, 2
	s_add_u32 s14, s14, 0x100
	s_addc_u32 s15, s15, 0
	s_add_u32 vcc_hi, vcc_hi, 0x100
	s_addc_u32 s24, s24, 0
	s_cmp_gt_u32 s25, 29
	s_cbranch_scc0 .LBB0_684
	s_and_b64 vcc, exec, s[52:53]
	s_cbranch_vccz .LBB0_687
	s_barrier

; #define PG8_STAGE(bufoff, gbase, voff) do { _Pragma("unroll") for (int _i = 0; _i < 2; ++_i) _Pragma("unroll") for (int _r = 0; _r < PG8_NREP; ++_r) \
;         __builtin_amdgcn_global_load_lds((const unsigned*)((const char*)(gbase) + (voff)[_i]), (PG8_LAS unsigned*)(lds + (bufoff) + ldsw + _i * 8192), 16, 0, 0); } while (0)
; #define PG8_LDA(dst, b, h) do { _Pragma("unroll") for (int m = 0; m < 4; ++m) _Pragma("unroll") for (int k = 0; k < 2; ++k) { dst[m][k] = *(const PG8_LAS bf16x8*)(lds + PG8_SA(b, h) + aoff + m * 2048 + k * 1024); PG8_DUP((unsigned)(uintptr_t)(lds + PG8_SA(b, h) + aoff + m * 2048 + k * 1024)); } } while (0)
; #define PG8_LDB(dst, b, h) do { _Pragma("unroll") for (int n = 0; n < 2; ++n) _Pragma("unroll") for (int k = 0; k < 2; ++k) { dst[n][k] = *(const PG8_LAS bf16x8*)(lds + PG8_SB(b, h) + boff + n * 2048 + k * 1024); PG8_DUP((unsigned)(uintptr_t)(lds + PG8_SB(b, h) + boff + n * 2048 + k * 1024)); } } while (0)
; #define PG8_MMA(ai, bj, At, Bt) do { __builtin_amdgcn_s_setprio(1); _Pragma("unroll") for (int m = 0; m < 4; ++m) _Pragma("unroll") for (int n = 0; n < 2; ++n) _Pragma("unroll") for (int k = 0; k < 2; ++k) \
;         acc[ai][bj][m][n] = __builtin_amdgcn_mfma_f32_16x16x32_bf16(Bt[n][k], At[m][k], acc[ai][bj][m][n], 0, 0, 0); __builtin_amdgcn_s_setprio(0); } while (0)
; template <class Epi, class Sched, bool ALIGN_EPI = false, bool SP2 = false>
; __device__ __forceinline__ void gemm_phase(PG8_LAS unsigned char* lds, const Gemm g, const Sched& S, const Epi& E) {
;     ...
;             const bool last = (t == nt - 2);
;             const char* a1 = cA + (size_t)(t + 1) * kstep;
;             const char* a2 = last ? nA : cA + (size_t)(t + 2) * kstep; const char* b2 = last ? nB : cB + (size_t)(t + 2) * kstep;
;             const char* a3 = a2 + kstep; const char* b3 = b2 + kstep;
;             if (last && has_next) S.a_ready(nxt);
;             if constexpr (SP2) {
;     ...
;             if (Epi::PERM && sizeof(Epi) && TEST_DRAIN) PG8_WAIT_V(0);
;     ...
;             PG8_LDB(B0, 0, 0); PG8_LDB(B1, 0, 1); PG8_SCHED; PG8_LDA(At, 0, 0); PG8_STAGE(PG8_SA(1, 1), a1 + hstepA, voffA);
;             PG8_WAIT_V(8); PG8_WAIT_L(0); PG8_BAR; PG8_MMA(0, 0, At, B0); PG8_MMA(0, 1, At, B1); PG8_BAR; PG8_SCHED;
;             PG8_LDA(At, 0, 1); PG8_STAGE(PG8_SB(0, 0), b2, voffB); PG8_STAGE(PG8_SB(0, 1), b2 + hstepB, voffB); PG8_STAGE(PG8_SA(0, 0), a2, voffA);
.LBB0_772:
	s_add_u32 s26, s52, 0xfff80080
	s_addc_u32 s27, s53, -1
	s_add_i32 s28, 0, 0x10000
	s_cmp_eq_u32 s25, 28
	s_cselect_b32 s59, s47, s27
	s_cselect_b32 s58, s86, s26
	v_add_u32_e32 v142, s28, v145
	s_cselect_b32 s55, s45, s24
	s_cselect_b32 s54, s91, s92
	s_add_i32 s29, 0, 0x14000
	ds_read_b128 v[138:141], v142
	ds_read_b128 v[148:151], v142 offset:1024
	ds_read_b128 v[152:155], v142 offset:2048
	ds_read_b128 v[156:159], v142 offset:3072
	v_add_u32_e32 v142, s29, v145
	ds_read_b128 v[160:163], v142
	ds_read_b128 v[164:167], v142 offset:1024
	ds_read_b128 v[168:171], v142 offset:2048
	ds_read_b128 v[172:175], v142 offset:3072
	v_lshl_add_u64 v[142:143], s[52:53], 0, v[134:135]
	s_add_i32 m0, s17, 0xc000
	ds_read_b128 v[176:179], v147
	ds_read_b128 v[180:183], v147 offset:1024
	ds_read_b128 v[184:187], v147 offset:2048
	ds_read_b128 v[188:191], v147 offset:3072
	ds_read_b128 v[194:197], v147 offset:4096
	ds_read_b128 v[210:213], v147 offset:5120
	ds_read_b128 v[214:217], v147 offset:6144
	ds_read_b128 v[218:221], v147 offset:7168
	global_load_lds_dwordx4 v[142:143], off
	v_lshl_add_u64 v[142:143], s[52:53], 0, v[136:137]
	s_add_i32 m0, s17, 0xe000
	s_nop 0
	global_load_lds_dwordx4 v[142:143], off
	s_waitcnt vmcnt(8)
	s_waitcnt lgkmcnt(0)
	s_barrier
	s_setprio 1
	s_waitcnt lgkmcnt(0)
	v_mfma_f32_16x16x32_bf16 v[124:127], v[138:141], v[176:179], v[124:127]
	v_mfma_f32_16x16x32_bf16 v[120:123], v[152:155], v[176:179], v[120:123]
	v_mfma_f32_16x16x32_bf16 v[108:111], v[138:141], v[184:187], v[108:111]
	v_mfma_f32_16x16x32_bf16 v[104:107], v[152:155], v[184:187], v[104:107]
	v_mfma_f32_16x16x32_bf16 v[92:95], v[138:141], v[194:197], v[92:95]
	v_mfma_f32_16x16x32_bf16 v[88:91], v[152:155], v[194:197], v[88:91]
	v_mfma_f32_16x16x32_bf16 v[76:79], v[138:141], v[214:217], v[76:79]
	v_mfma_f32_16x16x32_bf16 v[72:75], v[152:155], v[214:217], v[72:75]
	v_mfma_f32_16x16x32_bf16 v[124:127], v[148:151], v[180:183], v[124:127]
	v_mfma_f32_16x16x32_bf16 v[120:123], v[156:159], v[180:183], v[120:123]
	v_mfma_f32_16x16x32_bf16 v[108:111], v[148:151], v[188:191], v[108:111]
	v_mfma_f32_16x16x32_bf16 v[104:107], v[156:159], v[188:191], v[104:107]
	v_mfma_f32_16x16x32_bf16 v[92:95], v[148:151], v[210:213], v[92:95]
	v_mfma_f32_16x16x32_bf16 v[88:91], v[156:159], v[210:213], v[88:91]
	v_mfma_f32_16x16x32_bf16 v[76:79], v[148:151], v[218:221], v[76:79]
	v_mfma_f32_16x16x32_bf16 v[72:75], v[156:159], v[218:221], v[72:75]
	v_mfma_f32_16x16x32_bf16 v[116:119], v[160:163], v[176:179], v[116:119]
	v_mfma_f32_16x16x32_bf16 v[112:115], v[168:171], v[176:179], v[112:115]
	v_mfma_f32_16x16x32_bf16 v[100:103], v[160:163], v[184:187], v[100:103]
	v_mfma_f32_16x16x32_bf16 v[96:99], v[168:171], v[184:187], v[96:99]
	v_mfma_f32_16x16x32_bf16 v[84:87], v[160:163], v[194:197], v[84:87]
	v_mfma_f32_16x16x32_bf16 v[80:83], v[168:171], v[194:197], v[80:83]
	v_mfma_f32_16x16x32_bf16 v[68:71], v[160:163], v[214:217], v[68:71]
	v_mfma_f32_16x16x32_bf16 v[64:67], v[168:171], v[214:217], v[64:67]
	v_mfma_f32_16x16x32_bf16 v[116:119], v[164:167], v[180:183], v[116:119]
	v_mfma_f32_16x16x32_bf16 v[112:115], v[172:175], v[180:183], v[112:115]
	v_mfma_f32_16x16x32_bf16 v[100:103], v[164:167], v[188:191], v[100:103]
	v_mfma_f32_16x16x32_bf16 v[96:99], v[172:175], v[188:191], v[96:99]
	v_mfma_f32_16x16x32_bf16 v[84:87], v[164:167], v[210:213], v[84:87]
	v_mfma_f32_16x16x32_bf16 v[80:83], v[172:175], v[210:213], v[80:83]
	v_mfma_f32_16x16x32_bf16 v[68:71], v[164:167], v[218:221], v[68:71]
	v_mfma_f32_16x16x32_bf16 v[64:67], v[172:175], v[218:221], v[64:67]
	s_setprio 0
	s_barrier
	s_add_i32 s26, s28, s16
	v_lshl_add_u64 v[142:143], s[54:55], 0, v[192:193]
	s_mov_b32 m0, s26
	ds_read_b128 v[176:179], v147 offset:16384
	ds_read_b128 v[180:183], v147 offset:17408
	ds_read_b128 v[184:187], v147 offset:18432
	ds_read_b128 v[188:191], v147 offset:19456
	ds_read_b128 v[194:197], v147 offset:20480
	ds_read_b128 v[210:213], v147 offset:21504
	ds_read_b128 v[214:217], v147 offset:22528
	ds_read_b128 v[218:221], v147 offset:23552
	global_load_lds_dwordx4 v[142:143], off
	s_add_i32 m0, s26, 0x2000
	s_add_u32 s26, s54, 0x80000
	v_lshl_add_u64 v[200:201], s[54:55], 0, v[128:129]
	s_addc_u32 s27, s55, 0
	s_add_i32 s28, s29, s16
	global_load_lds_dwordx4 v[200:201], off
	v_lshl_add_u64 v[222:223], s[26:27], 0, v[192:193]
	s_mov_b32 m0, s28
	v_lshl_add_u64 v[224:225], s[58:59], 0, v[130:131]
	global_load_lds_dwordx4 v[222:223], off
	v_lshl_add_u64 v[222:223], s[26:27], 0, v[128:129]
	s_add_i32 m0, s28, 0x2000
	s_nop 0
	global_load_lds_dwordx4 v[222:223], off
	v_lshl_add_u64 v[222:223], s[58:59], 0, v[132:133]
	s_mov_b32 m0, s17
	s_nop 0
	global_load_lds_dwordx4 v[222:223], off
	s_mov_b32 m0, s18
	s_nop 0
	global_load_lds_dwordx4 v[224:225], off
	s_waitcnt vmcnt(8)
	s_waitcnt lgkmcnt(0)
	s_barrier
; #define PG8_STAGE(bufoff, gbase, voff) do { _Pragma("unroll") for (int _i = 0; _i < 2; ++_i) _Pragma("unroll") for (int _r = 0; _r < PG8_NREP; ++_r) \
;         __builtin_amdgcn_global_load_lds((const unsigned*)((const char*)(gbase) + (voff)[_i]), (PG8_LAS unsigned*)(lds + (bufoff) + ldsw + _i * 8192), 16, 0, 0); } while (0)
; #define PG8_LDA(dst, b, h) do { _Pragma("unroll") for (int m = 0; m < 4; ++m) _Pragma("unroll") for (int k = 0; k < 2; ++k) { dst[m][k] = *(const PG8_LAS bf16x8*)(lds + PG8_SA(b, h) + aoff + m * 2048 + k * 1024); PG8_DUP((unsigned)(uintptr_t)(lds + PG8_SA(b, h) + aoff + m * 2048 + k * 1024)); } } while (0)
; #define PG8_LDB(dst, b, h) do { _Pragma("unroll") for (int n = 0; n < 2; ++n) _Pragma("unroll") for (int k = 0; k < 2; ++k) { dst[n][k] = *(const PG8_LAS bf16x8*)(lds + PG8_SB(b, h) + boff + n * 2048 + k * 1024); PG8_DUP((unsigned)(uintptr_t)(lds + PG8_SB(b, h) + boff + n * 2048 + k * 1024)); } } while (0)
; #define PG8_MMA(ai, bj, At, Bt) do { __builtin_amdgcn_s_setprio(1); _Pragma("unroll") for (int m = 0; m < 4; ++m) _Pragma("unroll") for (int n = 0; n < 2; ++n) _Pragma("unroll") for (int k = 0; k < 2; ++k) \
;         acc[ai][bj][m][n] = __builtin_amdgcn_mfma_f32_16x16x32_bf16(Bt[n][k], At[m][k], acc[ai][bj][m][n], 0, 0, 0); __builtin_amdgcn_s_setprio(0); } while (0)
; #define PG8_WAIT_V(n) do { if ((n) == 0) asm volatile("s_waitcnt vmcnt(0)" ::: "memory"); else if ((n) == 2) asm volatile("s_waitcnt vmcnt(4)" ::: "memory"); else if ((n) == 4) asm volatile("s_waitcnt vmcnt(8)" ::: "memory"); \
;     else if ((n) == 6) asm volatile("s_waitcnt vmcnt(12)" ::: "memory"); else asm volatile("s_waitcnt vmcnt(16)" ::: "memory"); } while (0)
; #define PG8_WAIT_V(n) asm volatile("s_waitcnt vmcnt(" #n ")" ::: "memory")
; #define PG8_BAR __builtin_amdgcn_s_barrier()
; template <class Epi, class Sched, bool ALIGN_EPI = false, bool SP2 = false>
; __device__ __forceinline__ void gemm_phase(PG8_LAS unsigned char* lds, const Gemm g, const Sched& S, const Epi& E) {
;     ...
;             PG8_WAIT_V(8); PG8_WAIT_L(0); PG8_BAR; PG8_MMA(1, 0, At, B0); PG8_MMA(1, 1, At, B1); PG8_BAR; PG8_SCHED;
;             PG8_LDB(B0, 1, 0); PG8_LDB(B1, 1, 1); PG8_SCHED; PG8_LDA(At, 1, 0); PG8_STAGE(PG8_SA(0, 1), a2 + hstepA, voffA);
;             PG8_WAIT_V(8); PG8_WAIT_L(0); PG8_BAR; PG8_MMA(0, 0, At, B0); PG8_MMA(0, 1, At, B1); PG8_BAR; PG8_SCHED;
	s_setprio 1
	s_waitcnt lgkmcnt(0)
	v_mfma_f32_16x16x32_bf16 v[60:63], v[138:141], v[176:179], v[60:63]
	v_mfma_f32_16x16x32_bf16 v[56:59], v[152:155], v[176:179], v[56:59]
	v_mfma_f32_16x16x32_bf16 v[44:47], v[138:141], v[184:187], v[44:47]
	v_mfma_f32_16x16x32_bf16 v[40:43], v[152:155], v[184:187], v[40:43]
	v_mfma_f32_16x16x32_bf16 v[28:31], v[138:141], v[194:197], v[28:31]
	v_mfma_f32_16x16x32_bf16 v[24:27], v[152:155], v[194:197], v[24:27]
	v_mfma_f32_16x16x32_bf16 v[12:15], v[138:141], v[214:217], v[12:15]
	v_mfma_f32_16x16x32_bf16 v[8:11], v[152:155], v[214:217], v[8:11]
	v_mfma_f32_16x16x32_bf16 v[60:63], v[148:151], v[180:183], v[60:63]
	v_mfma_f32_16x16x32_bf16 v[56:59], v[156:159], v[180:183], v[56:59]
	v_mfma_f32_16x16x32_bf16 v[44:47], v[148:151], v[188:191], v[44:47]
	v_mfma_f32_16x16x32_bf16 v[40:43], v[156:159], v[188:191], v[40:43]
	v_mfma_f32_16x16x32_bf16 v[28:31], v[148:151], v[210:213], v[28:31]
	v_mfma_f32_16x16x32_bf16 v[24:27], v[156:159], v[210:213], v[24:27]
	v_mfma_f32_16x16x32_bf16 v[12:15], v[148:151], v[218:221], v[12:15]
	v_mfma_f32_16x16x32_bf16 v[8:11], v[156:159], v[218:221], v[8:11]
	v_mfma_f32_16x16x32_bf16 v[52:55], v[160:163], v[176:179], v[52:55]
	v_mfma_f32_16x16x32_bf16 v[48:51], v[168:171], v[176:179], v[48:51]
	v_mfma_f32_16x16x32_bf16 v[36:39], v[160:163], v[184:187], v[36:39]
	v_mfma_f32_16x16x32_bf16 v[32:35], v[168:171], v[184:187], v[32:35]
	v_mfma_f32_16x16x32_bf16 v[20:23], v[160:163], v[194:197], v[20:23]
	v_mfma_f32_16x16x32_bf16 v[16:19], v[168:171], v[194:197], v[16:19]
	v_mfma_f32_16x16x32_bf16 v[4:7], v[160:163], v[214:217], v[4:7]
	v_mfma_f32_16x16x32_bf16 v[0:3], v[168:171], v[214:217], v[0:3]
	v_mfma_f32_16x16x32_bf16 v[52:55], v[164:167], v[180:183], v[52:55]
	v_mfma_f32_16x16x32_bf16 v[48:51], v[172:175], v[180:183], v[48:51]
	v_mfma_f32_16x16x32_bf16 v[36:39], v[164:167], v[188:191], v[36:39]
	v_mfma_f32_16x16x32_bf16 v[32:35], v[172:175], v[188:191], v[32:35]
	v_mfma_f32_16x16x32_bf16 v[20:23], v[164:167], v[210:213], v[20:23]
	v_mfma_f32_16x16x32_bf16 v[16:19], v[172:175], v[210:213], v[16:19]
	v_mfma_f32_16x16x32_bf16 v[4:7], v[164:167], v[218:221], v[4:7]
	v_mfma_f32_16x16x32_bf16 v[0:3], v[172:175], v[218:221], v[0:3]
	s_setprio 0
	s_barrier
	s_add_i32 s28, 0, 0x18000
	s_add_i32 s29, 0, 0x1c000
	v_add_u32_e32 v156, s28, v145
	v_add_u32_e32 v172, s29, v145
	ds_read_b128 v[138:141], v156
	ds_read_b128 v[148:151], v156 offset:1024
	ds_read_b128 v[152:155], v156 offset:2048
	ds_read_b128 v[156:159], v156 offset:3072
	ds_read_b128 v[160:163], v172
	ds_read_b128 v[164:167], v172 offset:1024
	ds_read_b128 v[168:171], v172 offset:2048
	ds_read_b128 v[172:175], v172 offset:3072
	s_add_u32 s26, s58, 0x80000
	s_addc_u32 s27, s59, 0
	s_mov_b32 m0, s19
	v_lshl_add_u64 v[226:227], s[26:27], 0, v[132:133]
	ds_read_b128 v[176:179], v147 offset:32768
	ds_read_b128 v[180:183], v147 offset:33792
	ds_read_b128 v[184:187], v147 offset:34816
	ds_read_b128 v[188:191], v147 offset:35840
	ds_read_b128 v[194:197], v147 offset:36864
	ds_read_b128 v[210:213], v147 offset:37888
	ds_read_b128 v[214:217], v147 offset:38912
	ds_read_b128 v[218:221], v147 offset:39936
	global_load_lds_dwordx4 v[226:227], off
	v_lshl_add_u64 v[226:227], s[26:27], 0, v[130:131]
	s_mov_b32 m0, s20
	s_nop 0
	global_load_lds_dwordx4 v[226:227], off
	s_waitcnt vmcnt(8)
	s_waitcnt lgkmcnt(0)
	s_barrier
	s_setprio 1
	s_waitcnt lgkmcnt(0)
	v_mfma_f32_16x16x32_bf16 v[124:127], v[138:141], v[176:179], v[124:127]
	v_mfma_f32_16x16x32_bf16 v[120:123], v[152:155], v[176:179], v[120:123]
	v_mfma_f32_16x16x32_bf16 v[108:111], v[138:141], v[184:187], v[108:111]
	v_mfma_f32_16x16x32_bf16 v[104:107], v[152:155], v[184:187], v[104:107]
	v_mfma_f32_16x16x32_bf16 v[92:95], v[138:141], v[194:197], v[92:95]
	v_mfma_f32_16x16x32_bf16 v[88:91], v[152:155], v[194:197], v[88:91]
	v_mfma_f32_16x16x32_bf16 v[76:79], v[138:141], v[214:217], v[76:79]
	v_mfma_f32_16x16x32_bf16 v[72:75], v[152:155], v[214:217], v[72:75]
	v_mfma_f32_16x16x32_bf16 v[124:127], v[148:151], v[180:183], v[124:127]
	v_mfma_f32_16x16x32_bf16 v[120:123], v[156:159], v[180:183], v[120:123]
	v_mfma_f32_16x16x32_bf16 v[108:111], v[148:151], v[188:191], v[108:111]
	v_mfma_f32_16x16x32_bf16 v[104:107], v[156:159], v[188:191], v[104:107]
	v_mfma_f32_16x16x32_bf16 v[92:95], v[148:151], v[210:213], v[92:95]
	v_mfma_f32_16x16x32_bf16 v[88:91], v[156:159], v[210:213], v[88:91]
	v_mfma_f32_16x16x32_bf16 v[76:79], v[148:151], v[218:221], v[76:79]
	v_mfma_f32_16x16x32_bf16 v[72:75], v[156:159], v[218:221], v[72:75]
	v_mfma_f32_16x16x32_bf16 v[116:119], v[160:163], v[176:179], v[116:119]
	v_mfma_f32_16x16x32_bf16 v[112:115], v[168:171], v[176:179], v[112:115]
	v_mfma_f32_16x16x32_bf16 v[100:103], v[160:163], v[184:187], v[100:103]
	v_mfma_f32_16x16x32_bf16 v[96:99], v[168:171], v[184:187], v[96:99]
	v_mfma_f32_16x16x32_bf16 v[84:87], v[160:163], v[194:197], v[84:87]
	v_mfma_f32_16x16x32_bf16 v[80:83], v[168:171], v[194:197], v[80:83]
	v_mfma_f32_16x16x32_bf16 v[68:71], v[160:163], v[214:217], v[68:71]
	v_mfma_f32_16x16x32_bf16 v[64:67], v[168:171], v[214:217], v[64:67]
	v_mfma_f32_16x16x32_bf16 v[116:119], v[164:167], v[180:183], v[116:119]
	v_mfma_f32_16x16x32_bf16 v[112:115], v[172:175], v[180:183], v[112:115]
	v_mfma_f32_16x16x32_bf16 v[100:103], v[164:167], v[188:191], v[100:103]
	v_mfma_f32_16x16x32_bf16 v[96:99], v[172:175], v[188:191], v[96:99]
	v_mfma_f32_16x16x32_bf16 v[84:87], v[164:167], v[210:213], v[84:87]
	v_mfma_f32_16x16x32_bf16 v[80:83], v[172:175], v[210:213], v[80:83]
	v_mfma_f32_16x16x32_bf16 v[68:71], v[164:167], v[218:221], v[68:71]
	v_mfma_f32_16x16x32_bf16 v[64:67], v[172:175], v[218:221], v[64:67]
	s_setprio 0
	s_barrier
; #define PG8_STAGE(bufoff, gbase, voff) do { _Pragma("unroll") for (int _i = 0; _i < 2; ++_i) _Pragma("unroll") for (int _r = 0; _r < PG8_NREP; ++_r) \
;         __builtin_amdgcn_global_load_lds((const unsigned*)((const char*)(gbase) + (voff)[_i]), (PG8_LAS unsigned*)(lds + (bufoff) + ldsw + _i * 8192), 16, 0, 0); } while (0)
; #define PG8_LDA(dst, b, h) do { _Pragma("unroll") for (int m = 0; m < 4; ++m) _Pragma("unroll") for (int k = 0; k < 2; ++k) { dst[m][k] = *(const PG8_LAS bf16x8*)(lds + PG8_SA(b, h) + aoff + m * 2048 + k * 1024); PG8_DUP((unsigned)(uintptr_t)(lds + PG8_SA(b, h) + aoff + m * 2048 + k * 1024)); } } while (0)
; #define PG8_MMA(ai, bj, At, Bt) do { __builtin_amdgcn_s_setprio(1); _Pragma("unroll") for (int m = 0; m < 4; ++m) _Pragma("unroll") for (int n = 0; n < 2; ++n) _Pragma("unroll") for (int k = 0; k < 2; ++k) \
;         acc[ai][bj][m][n] = __builtin_amdgcn_mfma_f32_16x16x32_bf16(Bt[n][k], At[m][k], acc[ai][bj][m][n], 0, 0, 0); __builtin_amdgcn_s_setprio(0); } while (0)
; #define PG8_WAIT_V(n) do { if ((n) == 0) asm volatile("s_waitcnt vmcnt(0)" ::: "memory"); else if ((n) == 2) asm volatile("s_waitcnt vmcnt(4)" ::: "memory"); else if ((n) == 4) asm volatile("s_waitcnt vmcnt(8)" ::: "memory"); \
;     else if ((n) == 6) asm volatile("s_waitcnt vmcnt(12)" ::: "memory"); else asm volatile("s_waitcnt vmcnt(16)" ::: "memory"); } while (0)
; #define PG8_WAIT_V(n) asm volatile("s_waitcnt vmcnt(" #n ")" ::: "memory")
; #define PG8_WAIT_L(n) asm volatile("s_waitcnt lgkmcnt(" #n ")" ::: "memory")
; #define PG8_BAR __builtin_amdgcn_s_barrier()
; #define PG8_SCHED __builtin_amdgcn_sched_barrier(0)
; template <class Epi, class Sched, bool ALIGN_EPI = false, bool SP2 = false>
; __device__ __forceinline__ void gemm_phase(PG8_LAS unsigned char* lds, const Gemm g, const Sched& S, const Epi& E) {
;     ...
;             PG8_LDA(At, 1, 1); PG8_STAGE(PG8_SB(1, 0), b3, voffB); PG8_STAGE(PG8_SB(1, 1), b3 + hstepB, voffB); PG8_STAGE(PG8_SA(1, 0), a3, voffA);
;             PG8_WAIT_V(8); PG8_WAIT_L(0); PG8_BAR; PG8_MMA(1, 0, At, B0); PG8_MMA(1, 1, At, B1); PG8_BAR; PG8_SCHED;
;     ...
;         if constexpr (ALIGN_EPI) { if (wr == 0) PG8_BAR; }
	s_add_i32 s26, s28, s16
	v_lshl_add_u64 v[142:143], v[142:143], 0, s[68:69]
	s_mov_b32 m0, s26
	ds_read_b128 v[176:179], v147 offset:49152
	ds_read_b128 v[180:183], v147 offset:50176
	ds_read_b128 v[184:187], v147 offset:51200
	ds_read_b128 v[188:191], v147 offset:52224
	ds_read_b128 v[194:197], v147 offset:53248
	ds_read_b128 v[210:213], v147 offset:54272
	ds_read_b128 v[214:217], v147 offset:55296
	ds_read_b128 v[218:221], v147 offset:56320
	global_load_lds_dwordx4 v[142:143], off
	s_add_i32 m0, s26, 0x2000
	s_add_u32 s26, s54, 0x80080
	v_lshl_add_u64 v[142:143], v[200:201], 0, s[68:69]
	s_addc_u32 s27, s55, 0
	s_add_i32 s28, s29, s16
	global_load_lds_dwordx4 v[142:143], off
	v_lshl_add_u64 v[142:143], s[26:27], 0, v[192:193]
	s_mov_b32 m0, s28
	s_nop 0
	global_load_lds_dwordx4 v[142:143], off
	v_lshl_add_u64 v[142:143], s[26:27], 0, v[128:129]
	s_add_i32 m0, s28, 0x2000
	s_nop 0
	global_load_lds_dwordx4 v[142:143], off
	v_lshl_add_u64 v[142:143], v[222:223], 0, s[68:69]
	s_mov_b32 m0, s21
	s_nop 0
	global_load_lds_dwordx4 v[142:143], off
	v_lshl_add_u64 v[142:143], v[224:225], 0, s[68:69]
	s_mov_b32 m0, s22
	s_nop 0
	global_load_lds_dwordx4 v[142:143], off
	s_waitcnt vmcnt(8)
	s_waitcnt lgkmcnt(0)
	s_barrier
	s_setprio 1
	s_waitcnt lgkmcnt(0)
	v_mfma_f32_16x16x32_bf16 v[60:63], v[138:141], v[176:179], v[60:63]
	v_mfma_f32_16x16x32_bf16 v[56:59], v[152:155], v[176:179], v[56:59]
	v_mfma_f32_16x16x32_bf16 v[44:47], v[138:141], v[184:187], v[44:47]
	v_mfma_f32_16x16x32_bf16 v[40:43], v[152:155], v[184:187], v[40:43]
	v_mfma_f32_16x16x32_bf16 v[28:31], v[138:141], v[194:197], v[28:31]
	v_mfma_f32_16x16x32_bf16 v[24:27], v[152:155], v[194:197], v[24:27]
	v_mfma_f32_16x16x32_bf16 v[12:15], v[138:141], v[214:217], v[12:15]
	v_mfma_f32_16x16x32_bf16 v[8:11], v[152:155], v[214:217], v[8:11]
	v_mfma_f32_16x16x32_bf16 v[60:63], v[148:151], v[180:183], v[60:63]
	v_mfma_f32_16x16x32_bf16 v[56:59], v[156:159], v[180:183], v[56:59]
	v_mfma_f32_16x16x32_bf16 v[44:47], v[148:151], v[188:191], v[44:47]
	v_mfma_f32_16x16x32_bf16 v[40:43], v[156:159], v[188:191], v[40:43]
	v_mfma_f32_16x16x32_bf16 v[28:31], v[148:151], v[210:213], v[28:31]
	v_mfma_f32_16x16x32_bf16 v[24:27], v[156:159], v[210:213], v[24:27]
	v_mfma_f32_16x16x32_bf16 v[12:15], v[148:151], v[218:221], v[12:15]
	v_mfma_f32_16x16x32_bf16 v[8:11], v[156:159], v[218:221], v[8:11]
	v_mfma_f32_16x16x32_bf16 v[52:55], v[160:163], v[176:179], v[52:55]
	v_mfma_f32_16x16x32_bf16 v[48:51], v[168:171], v[176:179], v[48:51]
	v_mfma_f32_16x16x32_bf16 v[36:39], v[160:163], v[184:187], v[36:39]
	v_mfma_f32_16x16x32_bf16 v[32:35], v[168:171], v[184:187], v[32:35]
	v_mfma_f32_16x16x32_bf16 v[20:23], v[160:163], v[194:197], v[20:23]
	v_mfma_f32_16x16x32_bf16 v[16:19], v[168:171], v[194:197], v[16:19]
	v_mfma_f32_16x16x32_bf16 v[4:7], v[160:163], v[214:217], v[4:7]
	v_mfma_f32_16x16x32_bf16 v[0:3], v[168:171], v[214:217], v[0:3]
	v_mfma_f32_16x16x32_bf16 v[52:55], v[164:167], v[180:183], v[52:55]
	v_mfma_f32_16x16x32_bf16 v[48:51], v[172:175], v[180:183], v[48:51]
	v_mfma_f32_16x16x32_bf16 v[36:39], v[164:167], v[188:191], v[36:39]
	v_mfma_f32_16x16x32_bf16 v[32:35], v[172:175], v[188:191], v[32:35]
	v_mfma_f32_16x16x32_bf16 v[20:23], v[164:167], v[210:213], v[20:23]
	v_mfma_f32_16x16x32_bf16 v[16:19], v[172:175], v[210:213], v[16:19]
	v_mfma_f32_16x16x32_bf16 v[4:7], v[164:167], v[218:221], v[4:7]
	v_mfma_f32_16x16x32_bf16 v[0:3], v[172:175], v[218:221], v[0:3]
	s_setprio 0
	s_barrier
	s_add_i32 s25, s25, 2
	s_add_u32 s52, s52, 0x100
	s_addc_u32 s53, s53, 0
	s_add_u32 s92, s92, 0x100
	s_addc_u32 s24, s24, 0
	s_cmp_gt_u32 s25, 29
	s_cbranch_scc0 .LBB0_772
	s_and_b64 vcc, exec, s[40:41]
	s_cbranch_vccz .LBB0_775
	s_barrier

; #define PG8_STAGE(bufoff, gbase, voff) do { _Pragma("unroll") for (int _i = 0; _i < 2; ++_i) _Pragma("unroll") for (int _r = 0; _r < PG8_NREP; ++_r) \
;         __builtin_amdgcn_global_load_lds((const unsigned*)((const char*)(gbase) + (voff)[_i]), (PG8_LAS unsigned*)(lds + (bufoff) + ldsw + _i * 8192), 16, 0, 0); } while (0)
; #define PG8_LDA(dst, b, h) do { _Pragma("unroll") for (int m = 0; m < 4; ++m) _Pragma("unroll") for (int k = 0; k < 2; ++k) { dst[m][k] = *(const PG8_LAS bf16x8*)(lds + PG8_SA(b, h) + aoff + m * 2048 + k * 1024); PG8_DUP((unsigned)(uintptr_t)(lds + PG8_SA(b, h) + aoff + m * 2048 + k * 1024)); } } while (0)
; #define PG8_LDB(dst, b, h) do { _Pragma("unroll") for (int n = 0; n < 2; ++n) _Pragma("unroll") for (int k = 0; k < 2; ++k) { dst[n][k] = *(const PG8_LAS bf16x8*)(lds + PG8_SB(b, h) + boff + n * 2048 + k * 1024); PG8_DUP((unsigned)(uintptr_t)(lds + PG8_SB(b, h) + boff + n * 2048 + k * 1024)); } } while (0)
; #define PG8_MMA(ai, bj, At, Bt) do { __builtin_amdgcn_s_setprio(1); _Pragma("unroll") for (int m = 0; m < 4; ++m) _Pragma("unroll") for (int n = 0; n < 2; ++n) _Pragma("unroll") for (int k = 0; k < 2; ++k) \
;         acc[ai][bj][m][n] = __builtin_amdgcn_mfma_f32_16x16x32_bf16(Bt[n][k], At[m][k], acc[ai][bj][m][n], 0, 0, 0); __builtin_amdgcn_s_setprio(0); } while (0)
; template <class Epi, class Sched, bool ALIGN_EPI = false, bool SP2 = false>
; __device__ __forceinline__ void gemm_phase(PG8_LAS unsigned char* lds, const Gemm g, const Sched& S, const Epi& E) {
;     ...
;             const bool last = (t == nt - 2);
;             const char* a1 = cA + (size_t)(t + 1) * kstep;
;             const char* a2 = last ? nA : cA + (size_t)(t + 2) * kstep; const char* b2 = last ? nB : cB + (size_t)(t + 2) * kstep;
;             const char* a3 = a2 + kstep; const char* b3 = b2 + kstep;
;             if (last && has_next) S.a_ready(nxt);
;             if constexpr (SP2) {
;     ...
;             if (Epi::PERM && sizeof(Epi) && TEST_DRAIN) PG8_WAIT_V(0);
;     ...
;             PG8_LDB(B0, 0, 0); PG8_LDB(B1, 0, 1); PG8_SCHED; PG8_LDA(At, 0, 0); PG8_STAGE(PG8_SA(1, 1), a1 + hstepA, voffA);
;             PG8_WAIT_V(8); PG8_WAIT_L(0); PG8_BAR; PG8_MMA(0, 0, At, B0); PG8_MMA(0, 1, At, B1); PG8_BAR; PG8_SCHED;
;             PG8_LDA(At, 0, 1); PG8_STAGE(PG8_SB(0, 0), b2, voffB); PG8_STAGE(PG8_SB(0, 1), b2 + hstepB, voffB); PG8_STAGE(PG8_SA(0, 0), a2, voffA);
.LBB0_845:
	s_add_u32 s26, s52, 0xffe00080
	s_addc_u32 s27, s53, -1
	s_add_i32 s28, 0, 0x10000
	s_cmpk_eq_i32 s25, 0x7c
	s_cselect_b32 s59, s47, s27
	s_cselect_b32 s58, s86, s26
	v_add_u32_e32 v142, s28, v145
	s_cselect_b32 s55, s45, s24
	s_cselect_b32 s54, s91, s92
	s_add_i32 s29, 0, 0x14000
	ds_read_b128 v[138:141], v142
	ds_read_b128 v[148:151], v142 offset:1024
	ds_read_b128 v[152:155], v142 offset:2048
	ds_read_b128 v[156:159], v142 offset:3072
	v_add_u32_e32 v142, s29, v145
	ds_read_b128 v[160:163], v142
	ds_read_b128 v[164:167], v142 offset:1024
	ds_read_b128 v[168:171], v142 offset:2048
	ds_read_b128 v[172:175], v142 offset:3072
	v_lshl_add_u64 v[142:143], s[52:53], 0, v[134:135]
	s_add_i32 m0, s17, 0xc000
	ds_read_b128 v[176:179], v147
	ds_read_b128 v[180:183], v147 offset:1024
	ds_read_b128 v[184:187], v147 offset:2048
	ds_read_b128 v[188:191], v147 offset:3072
	ds_read_b128 v[194:197], v147 offset:4096
	ds_read_b128 v[210:213], v147 offset:5120
	ds_read_b128 v[214:217], v147 offset:6144
	ds_read_b128 v[218:221], v147 offset:7168
	global_load_lds_dwordx4 v[142:143], off
	v_lshl_add_u64 v[142:143], s[52:53], 0, v[136:137]
	s_add_i32 m0, s17, 0xe000
	s_nop 0
	global_load_lds_dwordx4 v[142:143], off
	s_waitcnt vmcnt(8)
	s_waitcnt lgkmcnt(0)
	s_barrier
	s_setprio 1
	s_waitcnt lgkmcnt(0)
	v_mfma_f32_16x16x32_bf16 v[124:127], v[138:141], v[176:179], v[124:127]
	v_mfma_f32_16x16x32_bf16 v[120:123], v[152:155], v[176:179], v[120:123]
	v_mfma_f32_16x16x32_bf16 v[108:111], v[138:141], v[184:187], v[108:111]
	v_mfma_f32_16x16x32_bf16 v[104:107], v[152:155], v[184:187], v[104:107]
	v_mfma_f32_16x16x32_bf16 v[92:95], v[138:141], v[194:197], v[92:95]
	v_mfma_f32_16x16x32_bf16 v[88:91], v[152:155], v[194:197], v[88:91]
	v_mfma_f32_16x16x32_bf16 v[76:79], v[138:141], v[214:217], v[76:79]
	v_mfma_f32_16x16x32_bf16 v[72:75], v[152:155], v[214:217], v[72:75]
	v_mfma_f32_16x16x32_bf16 v[124:127], v[148:151], v[180:183], v[124:127]
	v_mfma_f32_16x16x32_bf16 v[120:123], v[156:159], v[180:183], v[120:123]
	v_mfma_f32_16x16x32_bf16 v[108:111], v[148:151], v[188:191], v[108:111]
	v_mfma_f32_16x16x32_bf16 v[104:107], v[156:159], v[188:191], v[104:107]
	v_mfma_f32_16x16x32_bf16 v[92:95], v[148:151], v[210:213], v[92:95]
	v_mfma_f32_16x16x32_bf16 v[88:91], v[156:159], v[210:213], v[88:91]
	v_mfma_f32_16x16x32_bf16 v[76:79], v[148:151], v[218:221], v[76:79]
	v_mfma_f32_16x16x32_bf16 v[72:75], v[156:159], v[218:221], v[72:75]
	v_mfma_f32_16x16x32_bf16 v[116:119], v[160:163], v[176:179], v[116:119]
	v_mfma_f32_16x16x32_bf16 v[112:115], v[168:171], v[176:179], v[112:115]
	v_mfma_f32_16x16x32_bf16 v[100:103], v[160:163], v[184:187], v[100:103]
	v_mfma_f32_16x16x32_bf16 v[96:99], v[168:171], v[184:187], v[96:99]
	v_mfma_f32_16x16x32_bf16 v[84:87], v[160:163], v[194:197], v[84:87]
	v_mfma_f32_16x16x32_bf16 v[80:83], v[168:171], v[194:197], v[80:83]
	v_mfma_f32_16x16x32_bf16 v[68:71], v[160:163], v[214:217], v[68:71]
	v_mfma_f32_16x16x32_bf16 v[64:67], v[168:171], v[214:217], v[64:67]
	v_mfma_f32_16x16x32_bf16 v[116:119], v[164:167], v[180:183], v[116:119]
	v_mfma_f32_16x16x32_bf16 v[112:115], v[172:175], v[180:183], v[112:115]
	v_mfma_f32_16x16x32_bf16 v[100:103], v[164:167], v[188:191], v[100:103]
	v_mfma_f32_16x16x32_bf16 v[96:99], v[172:175], v[188:191], v[96:99]
	v_mfma_f32_16x16x32_bf16 v[84:87], v[164:167], v[210:213], v[84:87]
	v_mfma_f32_16x16x32_bf16 v[80:83], v[172:175], v[210:213], v[80:83]
	v_mfma_f32_16x16x32_bf16 v[68:71], v[164:167], v[218:221], v[68:71]
	v_mfma_f32_16x16x32_bf16 v[64:67], v[172:175], v[218:221], v[64:67]
	s_setprio 0
	s_barrier
	s_add_i32 s26, s28, s16
	v_lshl_add_u64 v[142:143], s[54:55], 0, v[192:193]
	s_mov_b32 m0, s26
	ds_read_b128 v[176:179], v147 offset:16384
	ds_read_b128 v[180:183], v147 offset:17408
	ds_read_b128 v[184:187], v147 offset:18432
	ds_read_b128 v[188:191], v147 offset:19456
	ds_read_b128 v[194:197], v147 offset:20480
	ds_read_b128 v[210:213], v147 offset:21504
	ds_read_b128 v[214:217], v147 offset:22528
	ds_read_b128 v[218:221], v147 offset:23552
	global_load_lds_dwordx4 v[142:143], off
	s_add_i32 m0, s26, 0x2000
	s_add_u32 s26, s54, 0x200000
	v_lshl_add_u64 v[200:201], s[54:55], 0, v[128:129]
	s_addc_u32 s27, s55, 0
	s_add_i32 s28, s29, s16
	global_load_lds_dwordx4 v[200:201], off
	v_lshl_add_u64 v[222:223], s[26:27], 0, v[192:193]
	s_mov_b32 m0, s28
	v_lshl_add_u64 v[224:225], s[58:59], 0, v[130:131]
	global_load_lds_dwordx4 v[222:223], off
	v_lshl_add_u64 v[222:223], s[26:27], 0, v[128:129]
	s_add_i32 m0, s28, 0x2000
	s_nop 0
	global_load_lds_dwordx4 v[222:223], off
	v_lshl_add_u64 v[222:223], s[58:59], 0, v[132:133]
	s_mov_b32 m0, s17
	s_nop 0
	global_load_lds_dwordx4 v[222:223], off
	s_mov_b32 m0, s18
	s_nop 0
	global_load_lds_dwordx4 v[224:225], off
	s_waitcnt vmcnt(8)
	s_waitcnt lgkmcnt(0)
	s_barrier
; #define PG8_STAGE(bufoff, gbase, voff) do { _Pragma("unroll") for (int _i = 0; _i < 2; ++_i) _Pragma("unroll") for (int _r = 0; _r < PG8_NREP; ++_r) \
;         __builtin_amdgcn_global_load_lds((const unsigned*)((const char*)(gbase) + (voff)[_i]), (PG8_LAS unsigned*)(lds + (bufoff) + ldsw + _i * 8192), 16, 0, 0); } while (0)
; #define PG8_LDA(dst, b, h) do { _Pragma("unroll") for (int m = 0; m < 4; ++m) _Pragma("unroll") for (int k = 0; k < 2; ++k) { dst[m][k] = *(const PG8_LAS bf16x8*)(lds + PG8_SA(b, h) + aoff + m * 2048 + k * 1024); PG8_DUP((unsigned)(uintptr_t)(lds + PG8_SA(b, h) + aoff + m * 2048 + k * 1024)); } } while (0)
; #define PG8_LDB(dst, b, h) do { _Pragma("unroll") for (int n = 0; n < 2; ++n) _Pragma("unroll") for (int k = 0; k < 2; ++k) { dst[n][k] = *(const PG8_LAS bf16x8*)(lds + PG8_SB(b, h) + boff + n * 2048 + k * 1024); PG8_DUP((unsigned)(uintptr_t)(lds + PG8_SB(b, h) + boff + n * 2048 + k * 1024)); } } while (0)
; #define PG8_MMA(ai, bj, At, Bt) do { __builtin_amdgcn_s_setprio(1); _Pragma("unroll") for (int m = 0; m < 4; ++m) _Pragma("unroll") for (int n = 0; n < 2; ++n) _Pragma("unroll") for (int k = 0; k < 2; ++k) \
;         acc[ai][bj][m][n] = __builtin_amdgcn_mfma_f32_16x16x32_bf16(Bt[n][k], At[m][k], acc[ai][bj][m][n], 0, 0, 0); __builtin_amdgcn_s_setprio(0); } while (0)
; #define PG8_WAIT_V(n) do { if ((n) == 0) asm volatile("s_waitcnt vmcnt(0)" ::: "memory"); else if ((n) == 2) asm volatile("s_waitcnt vmcnt(4)" ::: "memory"); else if ((n) == 4) asm volatile("s_waitcnt vmcnt(8)" ::: "memory"); \
;     else if ((n) == 6) asm volatile("s_waitcnt vmcnt(12)" ::: "memory"); else asm volatile("s_waitcnt vmcnt(16)" ::: "memory"); } while (0)
; #define PG8_WAIT_V(n) asm volatile("s_waitcnt vmcnt(" #n ")" ::: "memory")
; #define PG8_BAR __builtin_amdgcn_s_barrier()
; template <class Epi, class Sched, bool ALIGN_EPI = false, bool SP2 = false>
; __device__ __forceinline__ void gemm_phase(PG8_LAS unsigned char* lds, const Gemm g, const Sched& S, const Epi& E) {
;     ...
;             PG8_WAIT_V(8); PG8_WAIT_L(0); PG8_BAR; PG8_MMA(1, 0, At, B0); PG8_MMA(1, 1, At, B1); PG8_BAR; PG8_SCHED;
;             PG8_LDB(B0, 1, 0); PG8_LDB(B1, 1, 1); PG8_SCHED; PG8_LDA(At, 1, 0); PG8_STAGE(PG8_SA(0, 1), a2 + hstepA, voffA);
;             PG8_WAIT_V(8); PG8_WAIT_L(0); PG8_BAR; PG8_MMA(0, 0, At, B0); PG8_MMA(0, 1, At, B1); PG8_BAR; PG8_SCHED;
	s_setprio 1
	s_waitcnt lgkmcnt(0)
	v_mfma_f32_16x16x32_bf16 v[60:63], v[138:141], v[176:179], v[60:63]
	v_mfma_f32_16x16x32_bf16 v[56:59], v[152:155], v[176:179], v[56:59]
	v_mfma_f32_16x16x32_bf16 v[44:47], v[138:141], v[184:187], v[44:47]
	v_mfma_f32_16x16x32_bf16 v[40:43], v[152:155], v[184:187], v[40:43]
	v_mfma_f32_16x16x32_bf16 v[28:31], v[138:141], v[194:197], v[28:31]
	v_mfma_f32_16x16x32_bf16 v[24:27], v[152:155], v[194:197], v[24:27]
	v_mfma_f32_16x16x32_bf16 v[12:15], v[138:141], v[214:217], v[12:15]
	v_mfma_f32_16x16x32_bf16 v[8:11], v[152:155], v[214:217], v[8:11]
	v_mfma_f32_16x16x32_bf16 v[60:63], v[148:151], v[180:183], v[60:63]
	v_mfma_f32_16x16x32_bf16 v[56:59], v[156:159], v[180:183], v[56:59]
	v_mfma_f32_16x16x32_bf16 v[44:47], v[148:151], v[188:191], v[44:47]
	v_mfma_f32_16x16x32_bf16 v[40:43], v[156:159], v[188:191], v[40:43]
	v_mfma_f32_16x16x32_bf16 v[28:31], v[148:151], v[210:213], v[28:31]
	v_mfma_f32_16x16x32_bf16 v[24:27], v[156:159], v[210:213], v[24:27]
	v_mfma_f32_16x16x32_bf16 v[12:15], v[148:151], v[218:221], v[12:15]
	v_mfma_f32_16x16x32_bf16 v[8:11], v[156:159], v[218:221], v[8:11]
	v_mfma_f32_16x16x32_bf16 v[52:55], v[160:163], v[176:179], v[52:55]
	v_mfma_f32_16x16x32_bf16 v[48:51], v[168:171], v[176:179], v[48:51]
	v_mfma_f32_16x16x32_bf16 v[36:39], v[160:163], v[184:187], v[36:39]
	v_mfma_f32_16x16x32_bf16 v[32:35], v[168:171], v[184:187], v[32:35]
	v_mfma_f32_16x16x32_bf16 v[20:23], v[160:163], v[194:197], v[20:23]
	v_mfma_f32_16x16x32_bf16 v[16:19], v[168:171], v[194:197], v[16:19]
	v_mfma_f32_16x16x32_bf16 v[4:7], v[160:163], v[214:217], v[4:7]
	v_mfma_f32_16x16x32_bf16 v[0:3], v[168:171], v[214:217], v[0:3]
	v_mfma_f32_16x16x32_bf16 v[52:55], v[164:167], v[180:183], v[52:55]
	v_mfma_f32_16x16x32_bf16 v[48:51], v[172:175], v[180:183], v[48:51]
	v_mfma_f32_16x16x32_bf16 v[36:39], v[164:167], v[188:191], v[36:39]
	v_mfma_f32_16x16x32_bf16 v[32:35], v[172:175], v[188:191], v[32:35]
	v_mfma_f32_16x16x32_bf16 v[20:23], v[164:167], v[210:213], v[20:23]
	v_mfma_f32_16x16x32_bf16 v[16:19], v[172:175], v[210:213], v[16:19]
	v_mfma_f32_16x16x32_bf16 v[4:7], v[164:167], v[218:221], v[4:7]
	v_mfma_f32_16x16x32_bf16 v[0:3], v[172:175], v[218:221], v[0:3]
	s_setprio 0
	s_barrier
	s_add_i32 s28, 0, 0x18000
	s_add_i32 s29, 0, 0x1c000
	v_add_u32_e32 v156, s28, v145
	v_add_u32_e32 v172, s29, v145
	ds_read_b128 v[138:141], v156
	ds_read_b128 v[148:151], v156 offset:1024
	ds_read_b128 v[152:155], v156 offset:2048
	ds_read_b128 v[156:159], v156 offset:3072
	ds_read_b128 v[160:163], v172
	ds_read_b128 v[164:167], v172 offset:1024
	ds_read_b128 v[168:171], v172 offset:2048
	ds_read_b128 v[172:175], v172 offset:3072
	s_add_u32 s26, s58, 0x200000
	s_addc_u32 s27, s59, 0
	s_mov_b32 m0, s19
	v_lshl_add_u64 v[226:227], s[26:27], 0, v[132:133]
	ds_read_b128 v[176:179], v147 offset:32768
	ds_read_b128 v[180:183], v147 offset:33792
	ds_read_b128 v[184:187], v147 offset:34816
	ds_read_b128 v[188:191], v147 offset:35840
	ds_read_b128 v[194:197], v147 offset:36864
	ds_read_b128 v[210:213], v147 offset:37888
	ds_read_b128 v[214:217], v147 offset:38912
	ds_read_b128 v[218:221], v147 offset:39936
	global_load_lds_dwordx4 v[226:227], off
	v_lshl_add_u64 v[226:227], s[26:27], 0, v[130:131]
	s_mov_b32 m0, s20
	s_nop 0
	global_load_lds_dwordx4 v[226:227], off
	s_waitcnt vmcnt(8)
	s_waitcnt lgkmcnt(0)
	s_barrier
	s_setprio 1
	s_waitcnt lgkmcnt(0)
	v_mfma_f32_16x16x32_bf16 v[124:127], v[138:141], v[176:179], v[124:127]
	v_mfma_f32_16x16x32_bf16 v[120:123], v[152:155], v[176:179], v[120:123]
	v_mfma_f32_16x16x32_bf16 v[108:111], v[138:141], v[184:187], v[108:111]
	v_mfma_f32_16x16x32_bf16 v[104:107], v[152:155], v[184:187], v[104:107]
	v_mfma_f32_16x16x32_bf16 v[92:95], v[138:141], v[194:197], v[92:95]
	v_mfma_f32_16x16x32_bf16 v[88:91], v[152:155], v[194:197], v[88:91]
	v_mfma_f32_16x16x32_bf16 v[76:79], v[138:141], v[214:217], v[76:79]
	v_mfma_f32_16x16x32_bf16 v[72:75], v[152:155], v[214:217], v[72:75]
	v_mfma_f32_16x16x32_bf16 v[124:127], v[148:151], v[180:183], v[124:127]
	v_mfma_f32_16x16x32_bf16 v[120:123], v[156:159], v[180:183], v[120:123]
	v_mfma_f32_16x16x32_bf16 v[108:111], v[148:151], v[188:191], v[108:111]
	v_mfma_f32_16x16x32_bf16 v[104:107], v[156:159], v[188:191], v[104:107]
	v_mfma_f32_16x16x32_bf16 v[92:95], v[148:151], v[210:213], v[92:95]
	v_mfma_f32_16x16x32_bf16 v[88:91], v[156:159], v[210:213], v[88:91]
	v_mfma_f32_16x16x32_bf16 v[76:79], v[148:151], v[218:221], v[76:79]
	v_mfma_f32_16x16x32_bf16 v[72:75], v[156:159], v[218:221], v[72:75]
	v_mfma_f32_16x16x32_bf16 v[116:119], v[160:163], v[176:179], v[116:119]
	v_mfma_f32_16x16x32_bf16 v[112:115], v[168:171], v[176:179], v[112:115]
	v_mfma_f32_16x16x32_bf16 v[100:103], v[160:163], v[184:187], v[100:103]
	v_mfma_f32_16x16x32_bf16 v[96:99], v[168:171], v[184:187], v[96:99]
	v_mfma_f32_16x16x32_bf16 v[84:87], v[160:163], v[194:197], v[84:87]
	v_mfma_f32_16x16x32_bf16 v[80:83], v[168:171], v[194:197], v[80:83]
	v_mfma_f32_16x16x32_bf16 v[68:71], v[160:163], v[214:217], v[68:71]
	v_mfma_f32_16x16x32_bf16 v[64:67], v[168:171], v[214:217], v[64:67]
	v_mfma_f32_16x16x32_bf16 v[116:119], v[164:167], v[180:183], v[116:119]
	v_mfma_f32_16x16x32_bf16 v[112:115], v[172:175], v[180:183], v[112:115]
	v_mfma_f32_16x16x32_bf16 v[100:103], v[164:167], v[188:191], v[100:103]
	v_mfma_f32_16x16x32_bf16 v[96:99], v[172:175], v[188:191], v[96:99]
	v_mfma_f32_16x16x32_bf16 v[84:87], v[164:167], v[210:213], v[84:87]
	v_mfma_f32_16x16x32_bf16 v[80:83], v[172:175], v[210:213], v[80:83]
	v_mfma_f32_16x16x32_bf16 v[68:71], v[164:167], v[218:221], v[68:71]
	v_mfma_f32_16x16x32_bf16 v[64:67], v[172:175], v[218:221], v[64:67]
	s_setprio 0
	s_barrier
; #define PG8_STAGE(bufoff, gbase, voff) do { _Pragma("unroll") for (int _i = 0; _i < 2; ++_i) _Pragma("unroll") for (int _r = 0; _r < PG8_NREP; ++_r) \
;         __builtin_amdgcn_global_load_lds((const unsigned*)((const char*)(gbase) + (voff)[_i]), (PG8_LAS unsigned*)(lds + (bufoff) + ldsw + _i * 8192), 16, 0, 0); } while (0)
; #define PG8_LDA(dst, b, h) do { _Pragma("unroll") for (int m = 0; m < 4; ++m) _Pragma("unroll") for (int k = 0; k < 2; ++k) { dst[m][k] = *(const PG8_LAS bf16x8*)(lds + PG8_SA(b, h) + aoff + m * 2048 + k * 1024); PG8_DUP((unsigned)(uintptr_t)(lds + PG8_SA(b, h) + aoff + m * 2048 + k * 1024)); } } while (0)
; #define PG8_MMA(ai, bj, At, Bt) do { __builtin_amdgcn_s_setprio(1); _Pragma("unroll") for (int m = 0; m < 4; ++m) _Pragma("unroll") for (int n = 0; n < 2; ++n) _Pragma("unroll") for (int k = 0; k < 2; ++k) \
;         acc[ai][bj][m][n] = __builtin_amdgcn_mfma_f32_16x16x32_bf16(Bt[n][k], At[m][k], acc[ai][bj][m][n], 0, 0, 0); __builtin_amdgcn_s_setprio(0); } while (0)
; #define PG8_WAIT_V(n) do { if ((n) == 0) asm volatile("s_waitcnt vmcnt(0)" ::: "memory"); else if ((n) == 2) asm volatile("s_waitcnt vmcnt(4)" ::: "memory"); else if ((n) == 4) asm volatile("s_waitcnt vmcnt(8)" ::: "memory"); \
;     else if ((n) == 6) asm volatile("s_waitcnt vmcnt(12)" ::: "memory"); else asm volatile("s_waitcnt vmcnt(16)" ::: "memory"); } while (0)
; #define PG8_WAIT_V(n) asm volatile("s_waitcnt vmcnt(" #n ")" ::: "memory")
; #define PG8_WAIT_L(n) asm volatile("s_waitcnt lgkmcnt(" #n ")" ::: "memory")
; #define PG8_BAR __builtin_amdgcn_s_barrier()
; #define PG8_SCHED __builtin_amdgcn_sched_barrier(0)
; template <class Epi, class Sched, bool ALIGN_EPI = false, bool SP2 = false>
; __device__ __forceinline__ void gemm_phase(PG8_LAS unsigned char* lds, const Gemm g, const Sched& S, const Epi& E) {
;     ...
;             PG8_LDA(At, 1, 1); PG8_STAGE(PG8_SB(1, 0), b3, voffB); PG8_STAGE(PG8_SB(1, 1), b3 + hstepB, voffB); PG8_STAGE(PG8_SA(1, 0), a3, voffA);
;             PG8_WAIT_V(8); PG8_WAIT_L(0); PG8_BAR; PG8_MMA(1, 0, At, B0); PG8_MMA(1, 1, At, B1); PG8_BAR; PG8_SCHED;
;     ...
;         if constexpr (ALIGN_EPI) { if (wr == 0) PG8_BAR; }
	s_add_i32 s26, s28, s16
	v_lshl_add_u64 v[142:143], v[142:143], 0, s[68:69]
	s_mov_b32 m0, s26
	ds_read_b128 v[176:179], v147 offset:49152
	ds_read_b128 v[180:183], v147 offset:50176
	ds_read_b128 v[184:187], v147 offset:51200
	ds_read_b128 v[188:191], v147 offset:52224
	ds_read_b128 v[194:197], v147 offset:53248
	ds_read_b128 v[210:213], v147 offset:54272
	ds_read_b128 v[214:217], v147 offset:55296
	ds_read_b128 v[218:221], v147 offset:56320
	global_load_lds_dwordx4 v[142:143], off
	s_add_i32 m0, s26, 0x2000
	s_add_u32 s26, s54, 0x200080
	v_lshl_add_u64 v[142:143], v[200:201], 0, s[68:69]
	s_addc_u32 s27, s55, 0
	s_add_i32 s28, s29, s16
	global_load_lds_dwordx4 v[142:143], off
	v_lshl_add_u64 v[142:143], s[26:27], 0, v[192:193]
	s_mov_b32 m0, s28
	s_nop 0
	global_load_lds_dwordx4 v[142:143], off
	v_lshl_add_u64 v[142:143], s[26:27], 0, v[128:129]
	s_add_i32 m0, s28, 0x2000
	s_nop 0
	global_load_lds_dwordx4 v[142:143], off
	v_lshl_add_u64 v[142:143], v[222:223], 0, s[68:69]
	s_mov_b32 m0, s21
	s_nop 0
	global_load_lds_dwordx4 v[142:143], off
	v_lshl_add_u64 v[142:143], v[224:225], 0, s[68:69]
	s_mov_b32 m0, s22
	s_nop 0
	global_load_lds_dwordx4 v[142:143], off
	s_waitcnt vmcnt(8)
	s_waitcnt lgkmcnt(0)
	s_barrier
	s_setprio 1
	s_waitcnt lgkmcnt(0)
	v_mfma_f32_16x16x32_bf16 v[60:63], v[138:141], v[176:179], v[60:63]
	v_mfma_f32_16x16x32_bf16 v[56:59], v[152:155], v[176:179], v[56:59]
	v_mfma_f32_16x16x32_bf16 v[44:47], v[138:141], v[184:187], v[44:47]
	v_mfma_f32_16x16x32_bf16 v[40:43], v[152:155], v[184:187], v[40:43]
	v_mfma_f32_16x16x32_bf16 v[28:31], v[138:141], v[194:197], v[28:31]
	v_mfma_f32_16x16x32_bf16 v[24:27], v[152:155], v[194:197], v[24:27]
	v_mfma_f32_16x16x32_bf16 v[12:15], v[138:141], v[214:217], v[12:15]
	v_mfma_f32_16x16x32_bf16 v[8:11], v[152:155], v[214:217], v[8:11]
	v_mfma_f32_16x16x32_bf16 v[60:63], v[148:151], v[180:183], v[60:63]
	v_mfma_f32_16x16x32_bf16 v[56:59], v[156:159], v[180:183], v[56:59]
	v_mfma_f32_16x16x32_bf16 v[44:47], v[148:151], v[188:191], v[44:47]
	v_mfma_f32_16x16x32_bf16 v[40:43], v[156:159], v[188:191], v[40:43]
	v_mfma_f32_16x16x32_bf16 v[28:31], v[148:151], v[210:213], v[28:31]
	v_mfma_f32_16x16x32_bf16 v[24:27], v[156:159], v[210:213], v[24:27]
	v_mfma_f32_16x16x32_bf16 v[12:15], v[148:151], v[218:221], v[12:15]
	v_mfma_f32_16x16x32_bf16 v[8:11], v[156:159], v[218:221], v[8:11]
	v_mfma_f32_16x16x32_bf16 v[52:55], v[160:163], v[176:179], v[52:55]
	v_mfma_f32_16x16x32_bf16 v[48:51], v[168:171], v[176:179], v[48:51]
	v_mfma_f32_16x16x32_bf16 v[36:39], v[160:163], v[184:187], v[36:39]
	v_mfma_f32_16x16x32_bf16 v[32:35], v[168:171], v[184:187], v[32:35]
	v_mfma_f32_16x16x32_bf16 v[20:23], v[160:163], v[194:197], v[20:23]
	v_mfma_f32_16x16x32_bf16 v[16:19], v[168:171], v[194:197], v[16:19]
	v_mfma_f32_16x16x32_bf16 v[4:7], v[160:163], v[214:217], v[4:7]
	v_mfma_f32_16x16x32_bf16 v[0:3], v[168:171], v[214:217], v[0:3]
	v_mfma_f32_16x16x32_bf16 v[52:55], v[164:167], v[180:183], v[52:55]
	v_mfma_f32_16x16x32_bf16 v[48:51], v[172:175], v[180:183], v[48:51]
	v_mfma_f32_16x16x32_bf16 v[36:39], v[164:167], v[188:191], v[36:39]
	v_mfma_f32_16x16x32_bf16 v[32:35], v[172:175], v[188:191], v[32:35]
	v_mfma_f32_16x16x32_bf16 v[20:23], v[164:167], v[210:213], v[20:23]
	v_mfma_f32_16x16x32_bf16 v[16:19], v[172:175], v[210:213], v[16:19]
	v_mfma_f32_16x16x32_bf16 v[4:7], v[164:167], v[218:221], v[4:7]
	v_mfma_f32_16x16x32_bf16 v[0:3], v[172:175], v[218:221], v[0:3]
	s_setprio 0
	s_barrier
	s_add_i32 s25, s25, 2
	s_add_u32 s52, s52, 0x100
	s_addc_u32 s53, s53, 0
	s_add_u32 s92, s92, 0x100
	s_addc_u32 s24, s24, 0
	s_cmpk_gt_u32 s25, 0x7d
	s_cbranch_scc0 .LBB0_845
	s_and_b64 vcc, exec, s[42:43]
	s_cbranch_vccz .LBB0_848
	s_barrier
